# GEMM K-loops: per-segment s_setprio flips removed; one static priority raise for waves 4-7 per GEMM phase
# baseline (speedup 1.0000x reference)
.LBB0_213:
	s_and_b64 vcc, exec, s[0:1]
	s_cbranch_vccz .Lsp_B
	s_setprio 1

.LBB0_216:
	s_add_u32 s28, s50, 0xfff80080
	s_addc_u32 s29, s51, -1
	s_add_i32 s89, 0, 0x10000
	s_cmp_eq_u32 s88, 28
	s_cselect_b32 s53, s43, s29
	s_cselect_b32 s52, s84, s28
	s_cselect_b32 s29, s41, s87
	s_cselect_b32 s28, s85, s86
	s_add_i32 s92, 0, 0x14000
	v_add_u32_e32 v158, s89, v147
	v_add_u32_e32 v174, s92, v147
	ds_read_b128 v[142:145], v158
	ds_read_b128 v[150:153], v158 offset:1024
	ds_read_b128 v[154:157], v158 offset:2048
	ds_read_b128 v[158:161], v158 offset:3072
	ds_read_b128 v[162:165], v174
	ds_read_b128 v[166:169], v174 offset:1024
	ds_read_b128 v[170:173], v174 offset:2048
	ds_read_b128 v[174:177], v174 offset:3072
	v_lshl_add_u64 v[206:207], s[50:51], 0, v[138:139]
	s_add_i32 m0, s36, 0xc000
	ds_read_b128 v[178:181], v149
	ds_read_b128 v[182:185], v149 offset:1024
	ds_read_b128 v[186:189], v149 offset:2048
	ds_read_b128 v[190:193], v149 offset:3072
	ds_read_b128 v[194:197], v149 offset:4096
	ds_read_b128 v[198:201], v149 offset:5120
	ds_read_b128 v[202:205], v149 offset:6144
	ds_read_b128 v[224:227], v149 offset:7168
	global_load_lds_dwordx4 v[206:207], off
	v_lshl_add_u64 v[206:207], s[50:51], 0, v[140:141]
	s_add_i32 m0, s36, 0xe000
	s_nop 0
	global_load_lds_dwordx4 v[206:207], off
	s_waitcnt vmcnt(8)
	s_waitcnt lgkmcnt(0)
	s_barrier
	s_nop 0
	s_waitcnt lgkmcnt(0)
	v_mfma_f32_16x16x32_bf16 v[126:129], v[142:145], v[178:181], v[126:129]
	v_mfma_f32_16x16x32_bf16 v[122:125], v[154:157], v[178:181], v[122:125]
	v_mfma_f32_16x16x32_bf16 v[118:121], v[142:145], v[186:189], v[118:121]
	v_mfma_f32_16x16x32_bf16 v[110:113], v[154:157], v[186:189], v[110:113]
	v_mfma_f32_16x16x32_bf16 v[102:105], v[142:145], v[194:197], v[102:105]
	v_mfma_f32_16x16x32_bf16 v[94:97], v[154:157], v[194:197], v[94:97]
	v_mfma_f32_16x16x32_bf16 v[86:89], v[142:145], v[202:205], v[86:89]
	v_mfma_f32_16x16x32_bf16 v[78:81], v[154:157], v[202:205], v[78:81]
	v_mfma_f32_16x16x32_bf16 v[126:129], v[150:153], v[182:185], v[126:129]
	v_mfma_f32_16x16x32_bf16 v[122:125], v[158:161], v[182:185], v[122:125]
	v_mfma_f32_16x16x32_bf16 v[118:121], v[150:153], v[190:193], v[118:121]
	v_mfma_f32_16x16x32_bf16 v[110:113], v[158:161], v[190:193], v[110:113]
	v_mfma_f32_16x16x32_bf16 v[102:105], v[150:153], v[198:201], v[102:105]
	v_mfma_f32_16x16x32_bf16 v[94:97], v[158:161], v[198:201], v[94:97]
	v_mfma_f32_16x16x32_bf16 v[86:89], v[150:153], v[224:227], v[86:89]
	v_mfma_f32_16x16x32_bf16 v[78:81], v[158:161], v[224:227], v[78:81]
	s_nop 0
	s_nop 0
	v_mfma_f32_16x16x32_bf16 v[114:117], v[162:165], v[178:181], v[114:117]
	v_mfma_f32_16x16x32_bf16 v[106:109], v[170:173], v[178:181], v[106:109]
	v_mfma_f32_16x16x32_bf16 v[98:101], v[162:165], v[186:189], v[98:101]
	v_mfma_f32_16x16x32_bf16 v[90:93], v[170:173], v[186:189], v[90:93]
	v_mfma_f32_16x16x32_bf16 v[82:85], v[162:165], v[194:197], v[82:85]
	v_mfma_f32_16x16x32_bf16 v[74:77], v[170:173], v[194:197], v[74:77]
	v_mfma_f32_16x16x32_bf16 v[70:73], v[162:165], v[202:205], v[70:73]
	v_mfma_f32_16x16x32_bf16 v[66:69], v[170:173], v[202:205], v[66:69]
	v_mfma_f32_16x16x32_bf16 v[114:117], v[166:169], v[182:185], v[114:117]
	v_mfma_f32_16x16x32_bf16 v[106:109], v[174:177], v[182:185], v[106:109]
	v_mfma_f32_16x16x32_bf16 v[98:101], v[166:169], v[190:193], v[98:101]
	v_mfma_f32_16x16x32_bf16 v[90:93], v[174:177], v[190:193], v[90:93]
	v_mfma_f32_16x16x32_bf16 v[82:85], v[166:169], v[198:201], v[82:85]
	v_mfma_f32_16x16x32_bf16 v[74:77], v[174:177], v[198:201], v[74:77]
	v_mfma_f32_16x16x32_bf16 v[70:73], v[166:169], v[224:227], v[70:73]
	v_mfma_f32_16x16x32_bf16 v[66:69], v[174:177], v[224:227], v[66:69]
	s_nop 0
	s_barrier
	s_add_i32 s89, s89, s26
	v_lshl_add_u64 v[206:207], s[28:29], 0, v[134:135]
	s_mov_b32 m0, s89
	ds_read_b128 v[178:181], v149 offset:16384
	ds_read_b128 v[182:185], v149 offset:17408
	ds_read_b128 v[186:189], v149 offset:18432
	ds_read_b128 v[190:193], v149 offset:19456
	ds_read_b128 v[194:197], v149 offset:20480
	ds_read_b128 v[198:201], v149 offset:21504
	ds_read_b128 v[202:205], v149 offset:22528
	ds_read_b128 v[224:227], v149 offset:23552
	global_load_lds_dwordx4 v[206:207], off
	s_add_i32 m0, s89, 0x2000
	s_add_u32 s90, s28, 0x80000
	v_lshl_add_u64 v[228:229], s[28:29], 0, v[130:131]
	s_addc_u32 s91, s29, 0
	s_add_i32 s89, s92, s26
	global_load_lds_dwordx4 v[228:229], off
	v_lshl_add_u64 v[230:231], s[90:91], 0, v[134:135]
	s_mov_b32 m0, s89
	v_lshl_add_u64 v[232:233], s[52:53], 0, v[132:133]
	global_load_lds_dwordx4 v[230:231], off
	v_lshl_add_u64 v[230:231], s[90:91], 0, v[130:131]
	s_add_i32 m0, s89, 0x2000
	s_nop 0
	global_load_lds_dwordx4 v[230:231], off
	v_lshl_add_u64 v[230:231], s[52:53], 0, v[136:137]
	s_mov_b32 m0, s36
	s_nop 0
	global_load_lds_dwordx4 v[230:231], off
	s_mov_b32 m0, s37
	s_nop 0
	global_load_lds_dwordx4 v[232:233], off
	s_waitcnt vmcnt(8)
	s_waitcnt lgkmcnt(0)
	s_barrier
	s_nop 0
	s_waitcnt lgkmcnt(0)
	v_mfma_f32_16x16x32_bf16 v[62:65], v[142:145], v[178:181], v[62:65]
	v_mfma_f32_16x16x32_bf16 v[58:61], v[154:157], v[178:181], v[58:61]
	v_mfma_f32_16x16x32_bf16 v[54:57], v[142:145], v[186:189], v[54:57]
	v_mfma_f32_16x16x32_bf16 v[46:49], v[154:157], v[186:189], v[46:49]
	v_mfma_f32_16x16x32_bf16 v[38:41], v[142:145], v[194:197], v[38:41]
	v_mfma_f32_16x16x32_bf16 v[30:33], v[154:157], v[194:197], v[30:33]
	v_mfma_f32_16x16x32_bf16 v[22:25], v[142:145], v[202:205], v[22:25]
	v_mfma_f32_16x16x32_bf16 v[12:15], v[154:157], v[202:205], v[12:15]
	v_mfma_f32_16x16x32_bf16 v[62:65], v[150:153], v[182:185], v[62:65]
	v_mfma_f32_16x16x32_bf16 v[58:61], v[158:161], v[182:185], v[58:61]
	v_mfma_f32_16x16x32_bf16 v[54:57], v[150:153], v[190:193], v[54:57]
	v_mfma_f32_16x16x32_bf16 v[46:49], v[158:161], v[190:193], v[46:49]
	v_mfma_f32_16x16x32_bf16 v[38:41], v[150:153], v[198:201], v[38:41]
	v_mfma_f32_16x16x32_bf16 v[30:33], v[158:161], v[198:201], v[30:33]
	v_mfma_f32_16x16x32_bf16 v[22:25], v[150:153], v[224:227], v[22:25]
	v_mfma_f32_16x16x32_bf16 v[12:15], v[158:161], v[224:227], v[12:15]
	s_nop 0
	s_nop 0
	v_mfma_f32_16x16x32_bf16 v[50:53], v[162:165], v[178:181], v[50:53]
	v_mfma_f32_16x16x32_bf16 v[42:45], v[170:173], v[178:181], v[42:45]
	v_mfma_f32_16x16x32_bf16 v[34:37], v[162:165], v[186:189], v[34:37]
	v_mfma_f32_16x16x32_bf16 v[26:29], v[170:173], v[186:189], v[26:29]
	v_mfma_f32_16x16x32_bf16 v[18:21], v[162:165], v[194:197], v[18:21]
	v_mfma_f32_16x16x32_bf16 v[8:11], v[170:173], v[194:197], v[8:11]
	v_mfma_f32_16x16x32_bf16 v[4:7], v[162:165], v[202:205], v[4:7]
	v_mfma_f32_16x16x32_bf16 v[0:3], v[170:173], v[202:205], v[0:3]
	v_mfma_f32_16x16x32_bf16 v[50:53], v[166:169], v[182:185], v[50:53]
	v_mfma_f32_16x16x32_bf16 v[42:45], v[174:177], v[182:185], v[42:45]
	v_mfma_f32_16x16x32_bf16 v[34:37], v[166:169], v[190:193], v[34:37]
	v_mfma_f32_16x16x32_bf16 v[26:29], v[174:177], v[190:193], v[26:29]
	v_mfma_f32_16x16x32_bf16 v[18:21], v[166:169], v[198:201], v[18:21]
	v_mfma_f32_16x16x32_bf16 v[8:11], v[174:177], v[198:201], v[8:11]
	v_mfma_f32_16x16x32_bf16 v[4:7], v[166:169], v[224:227], v[4:7]
	v_mfma_f32_16x16x32_bf16 v[0:3], v[174:177], v[224:227], v[0:3]
	s_nop 0
	s_barrier
	s_add_i32 s89, 0, 0x18000
	s_add_i32 s90, 0, 0x1c000
	v_add_u32_e32 v158, s89, v147
	v_add_u32_e32 v174, s90, v147
	ds_read_b128 v[142:145], v158
	ds_read_b128 v[150:153], v158 offset:1024
	ds_read_b128 v[154:157], v158 offset:2048
	ds_read_b128 v[158:161], v158 offset:3072
	ds_read_b128 v[162:165], v174
	ds_read_b128 v[166:169], v174 offset:1024
	ds_read_b128 v[170:173], v174 offset:2048
	ds_read_b128 v[174:177], v174 offset:3072
	s_add_u32 s52, s52, 0x80000
	s_addc_u32 s53, s53, 0
	s_mov_b32 m0, s49
	v_lshl_add_u64 v[234:235], s[52:53], 0, v[136:137]
	ds_read_b128 v[178:181], v149 offset:32768
	ds_read_b128 v[182:185], v149 offset:33792
	ds_read_b128 v[186:189], v149 offset:34816
	ds_read_b128 v[190:193], v149 offset:35840
	ds_read_b128 v[194:197], v149 offset:36864
	ds_read_b128 v[198:201], v149 offset:37888
	ds_read_b128 v[202:205], v149 offset:38912
	ds_read_b128 v[224:227], v149 offset:39936
	global_load_lds_dwordx4 v[234:235], off
	v_lshl_add_u64 v[234:235], s[52:53], 0, v[132:133]
	s_mov_b32 m0, s56
	s_nop 0
	global_load_lds_dwordx4 v[234:235], off
	s_waitcnt vmcnt(8)
	s_waitcnt lgkmcnt(0)
	s_barrier
	s_nop 0
	s_waitcnt lgkmcnt(0)
	v_mfma_f32_16x16x32_bf16 v[126:129], v[142:145], v[178:181], v[126:129]
	v_mfma_f32_16x16x32_bf16 v[122:125], v[154:157], v[178:181], v[122:125]
	v_mfma_f32_16x16x32_bf16 v[118:121], v[142:145], v[186:189], v[118:121]
	v_mfma_f32_16x16x32_bf16 v[110:113], v[154:157], v[186:189], v[110:113]
	v_mfma_f32_16x16x32_bf16 v[102:105], v[142:145], v[194:197], v[102:105]
	v_mfma_f32_16x16x32_bf16 v[94:97], v[154:157], v[194:197], v[94:97]
	v_mfma_f32_16x16x32_bf16 v[86:89], v[142:145], v[202:205], v[86:89]
	v_mfma_f32_16x16x32_bf16 v[78:81], v[154:157], v[202:205], v[78:81]
	v_mfma_f32_16x16x32_bf16 v[126:129], v[150:153], v[182:185], v[126:129]
	v_mfma_f32_16x16x32_bf16 v[122:125], v[158:161], v[182:185], v[122:125]
	v_mfma_f32_16x16x32_bf16 v[118:121], v[150:153], v[190:193], v[118:121]
	v_mfma_f32_16x16x32_bf16 v[110:113], v[158:161], v[190:193], v[110:113]
	v_mfma_f32_16x16x32_bf16 v[102:105], v[150:153], v[198:201], v[102:105]
	v_mfma_f32_16x16x32_bf16 v[94:97], v[158:161], v[198:201], v[94:97]
	v_mfma_f32_16x16x32_bf16 v[86:89], v[150:153], v[224:227], v[86:89]
	v_mfma_f32_16x16x32_bf16 v[78:81], v[158:161], v[224:227], v[78:81]
	s_nop 0
	s_nop 0
	v_mfma_f32_16x16x32_bf16 v[114:117], v[162:165], v[178:181], v[114:117]
	v_mfma_f32_16x16x32_bf16 v[106:109], v[170:173], v[178:181], v[106:109]
	v_mfma_f32_16x16x32_bf16 v[98:101], v[162:165], v[186:189], v[98:101]
	v_mfma_f32_16x16x32_bf16 v[90:93], v[170:173], v[186:189], v[90:93]
	v_mfma_f32_16x16x32_bf16 v[82:85], v[162:165], v[194:197], v[82:85]
	v_mfma_f32_16x16x32_bf16 v[74:77], v[170:173], v[194:197], v[74:77]
	v_mfma_f32_16x16x32_bf16 v[70:73], v[162:165], v[202:205], v[70:73]
	v_mfma_f32_16x16x32_bf16 v[66:69], v[170:173], v[202:205], v[66:69]
	v_mfma_f32_16x16x32_bf16 v[114:117], v[166:169], v[182:185], v[114:117]
	v_mfma_f32_16x16x32_bf16 v[106:109], v[174:177], v[182:185], v[106:109]
	v_mfma_f32_16x16x32_bf16 v[98:101], v[166:169], v[190:193], v[98:101]
	v_mfma_f32_16x16x32_bf16 v[90:93], v[174:177], v[190:193], v[90:93]
	v_mfma_f32_16x16x32_bf16 v[82:85], v[166:169], v[198:201], v[82:85]
	v_mfma_f32_16x16x32_bf16 v[74:77], v[174:177], v[198:201], v[74:77]
	v_mfma_f32_16x16x32_bf16 v[70:73], v[166:169], v[224:227], v[70:73]
	v_mfma_f32_16x16x32_bf16 v[66:69], v[174:177], v[224:227], v[66:69]
	s_nop 0
	s_barrier
	s_add_i32 s52, s89, s26
	v_lshl_add_u64 v[206:207], v[206:207], 0, s[34:35]
	s_mov_b32 m0, s52
	ds_read_b128 v[178:181], v149 offset:49152
	ds_read_b128 v[182:185], v149 offset:50176
	ds_read_b128 v[186:189], v149 offset:51200
	ds_read_b128 v[190:193], v149 offset:52224
	ds_read_b128 v[194:197], v149 offset:53248
	ds_read_b128 v[198:201], v149 offset:54272
	ds_read_b128 v[202:205], v149 offset:55296
	ds_read_b128 v[224:227], v149 offset:56320
	global_load_lds_dwordx4 v[206:207], off
	s_add_i32 m0, s52, 0x2000
	s_add_u32 s28, s28, 0x80080
	v_lshl_add_u64 v[206:207], v[228:229], 0, s[34:35]
	s_addc_u32 s29, s29, 0
	s_add_i32 s52, s90, s26
	global_load_lds_dwordx4 v[206:207], off
	v_lshl_add_u64 v[206:207], s[28:29], 0, v[134:135]
	s_mov_b32 m0, s52
	s_nop 0
	global_load_lds_dwordx4 v[206:207], off
	v_lshl_add_u64 v[206:207], s[28:29], 0, v[130:131]
	s_add_i32 m0, s52, 0x2000
	s_nop 0
	global_load_lds_dwordx4 v[206:207], off
	v_lshl_add_u64 v[206:207], v[230:231], 0, s[34:35]
	s_mov_b32 m0, s57
	s_nop 0
	global_load_lds_dwordx4 v[206:207], off
	v_lshl_add_u64 v[206:207], v[232:233], 0, s[34:35]
	s_mov_b32 m0, s58
	s_nop 0
	global_load_lds_dwordx4 v[206:207], off
	s_waitcnt vmcnt(8)
	s_waitcnt lgkmcnt(0)
	s_barrier
	s_nop 0
	s_waitcnt lgkmcnt(0)
	v_mfma_f32_16x16x32_bf16 v[62:65], v[142:145], v[178:181], v[62:65]
	v_mfma_f32_16x16x32_bf16 v[58:61], v[154:157], v[178:181], v[58:61]
	v_mfma_f32_16x16x32_bf16 v[54:57], v[142:145], v[186:189], v[54:57]
	v_mfma_f32_16x16x32_bf16 v[46:49], v[154:157], v[186:189], v[46:49]
	v_mfma_f32_16x16x32_bf16 v[38:41], v[142:145], v[194:197], v[38:41]
	v_mfma_f32_16x16x32_bf16 v[30:33], v[154:157], v[194:197], v[30:33]
	v_mfma_f32_16x16x32_bf16 v[22:25], v[142:145], v[202:205], v[22:25]
	v_mfma_f32_16x16x32_bf16 v[12:15], v[154:157], v[202:205], v[12:15]
	v_mfma_f32_16x16x32_bf16 v[62:65], v[150:153], v[182:185], v[62:65]
	v_mfma_f32_16x16x32_bf16 v[58:61], v[158:161], v[182:185], v[58:61]
	v_mfma_f32_16x16x32_bf16 v[54:57], v[150:153], v[190:193], v[54:57]
	v_mfma_f32_16x16x32_bf16 v[46:49], v[158:161], v[190:193], v[46:49]
	v_mfma_f32_16x16x32_bf16 v[38:41], v[150:153], v[198:201], v[38:41]
	v_mfma_f32_16x16x32_bf16 v[30:33], v[158:161], v[198:201], v[30:33]
	v_mfma_f32_16x16x32_bf16 v[22:25], v[150:153], v[224:227], v[22:25]
	v_mfma_f32_16x16x32_bf16 v[12:15], v[158:161], v[224:227], v[12:15]
	s_nop 0
	s_nop 0
	v_mfma_f32_16x16x32_bf16 v[50:53], v[162:165], v[178:181], v[50:53]
	v_mfma_f32_16x16x32_bf16 v[42:45], v[170:173], v[178:181], v[42:45]
	v_mfma_f32_16x16x32_bf16 v[34:37], v[162:165], v[186:189], v[34:37]
	v_mfma_f32_16x16x32_bf16 v[26:29], v[170:173], v[186:189], v[26:29]
	v_mfma_f32_16x16x32_bf16 v[18:21], v[162:165], v[194:197], v[18:21]
	v_mfma_f32_16x16x32_bf16 v[8:11], v[170:173], v[194:197], v[8:11]
	v_mfma_f32_16x16x32_bf16 v[4:7], v[162:165], v[202:205], v[4:7]
	v_mfma_f32_16x16x32_bf16 v[0:3], v[170:173], v[202:205], v[0:3]
	v_mfma_f32_16x16x32_bf16 v[50:53], v[166:169], v[182:185], v[50:53]
	v_mfma_f32_16x16x32_bf16 v[42:45], v[174:177], v[182:185], v[42:45]
	v_mfma_f32_16x16x32_bf16 v[34:37], v[166:169], v[190:193], v[34:37]
	v_mfma_f32_16x16x32_bf16 v[26:29], v[174:177], v[190:193], v[26:29]
	v_mfma_f32_16x16x32_bf16 v[18:21], v[166:169], v[198:201], v[18:21]
	v_mfma_f32_16x16x32_bf16 v[8:11], v[174:177], v[198:201], v[8:11]
	v_mfma_f32_16x16x32_bf16 v[4:7], v[166:169], v[224:227], v[4:7]
	v_mfma_f32_16x16x32_bf16 v[0:3], v[174:177], v[224:227], v[0:3]
	s_nop 0
	s_barrier
	s_add_i32 s88, s88, 2
	s_add_u32 s50, s50, 0x100
	s_addc_u32 s51, s51, 0
	s_add_u32 s86, s86, 0x100
	s_addc_u32 s87, s87, 0
	s_cmp_gt_u32 s88, 29
	s_cbranch_scc0 .LBB0_216
	s_and_b64 vcc, exec, s[18:19]
	s_cbranch_vccz .LBB0_221
	s_barrier
	s_cmp_gt_i32 s83, 13
	s_mov_b64 s[28:29], -1
	s_cbranch_scc1 .LBB0_222

.LBB0_226:
	s_setprio 0
	s_waitcnt vmcnt(0)
	s_barrier
	v_readlane_b32 s86, v255, 41
	s_cmp_lg_u32 s86, 0
	s_cbranch_scc1 .Ldc_g0_skip
	s_movk_i32 s87, 128
	s_cmp_gt_u32 s60, s87
	s_cselect_b32 s87, s87, 0
	s_cmp_lt_u32 s2, s87
	s_cbranch_scc1 .Ldc_g0_skip
	v_writelane_b32 v255, s24, 48
	v_writelane_b32 v255, s28, 49
	v_writelane_b32 v255, s29, 50
	v_writelane_b32 v255, s37, 51
	v_writelane_b32 v255, s40, 52
	v_writelane_b32 v255, s41, 53
	v_writelane_b32 v255, s42, 54
	v_writelane_b32 v255, s43, 55
	v_writelane_b32 v255, s44, 56
	v_writelane_b32 v255, s48, 57
	v_writelane_b32 v255, s49, 58
	v_writelane_b32 v255, s87, 47
	s_sub_u32 s2, s2, s87
	s_sub_u32 s60, s60, s87
	v_readlane_b32 s18, v255, 8
	v_readlane_b32 s19, v255, 9
	s_load_dwordx2 s[42:43], s[18:19], 0xc0
	s_nop 0
	s_load_dwordx2 s[18:19], s[18:19], 0xf0
	s_waitcnt lgkmcnt(0)

.LBB0_649:
	s_add_u32 s28, s40, 0xfff80080
	s_addc_u32 s29, s41, -1
	s_add_i32 s88, 0, 0x10000
	s_cmp_eq_u32 s87, 4
	s_cselect_b32 s47, s27, s29
	s_cselect_b32 s46, s26, s28
	v_add_u32_e32 v140, s88, v143
	s_cselect_b32 s29, s19, s49
	s_cselect_b32 s28, s23, s48
	s_add_i32 s90, 0, 0x14000
	ds_read_b128 v[146:149], v140
	ds_read_b128 v[150:153], v140 offset:1024
	ds_read_b128 v[154:157], v140 offset:2048
	ds_read_b128 v[158:161], v140 offset:3072
	v_add_u32_e32 v140, s90, v143
	ds_read_b128 v[162:165], v140
	ds_read_b128 v[166:169], v140 offset:1024
	ds_read_b128 v[170:173], v140 offset:2048
	ds_read_b128 v[174:177], v140 offset:3072
	v_lshl_add_u64 v[140:141], s[40:41], 0, v[136:137]
	s_add_i32 m0, s45, 0xc000
	ds_read_b128 v[178:181], v145
	ds_read_b128 v[182:185], v145 offset:1024
	ds_read_b128 v[186:189], v145 offset:2048
	ds_read_b128 v[190:193], v145 offset:3072
	ds_read_b128 v[194:197], v145 offset:4096
	ds_read_b128 v[198:201], v145 offset:5120
	ds_read_b128 v[202:205], v145 offset:6144
	ds_read_b128 v[224:227], v145 offset:7168
	global_load_lds_dwordx4 v[140:141], off
	v_lshl_add_u64 v[140:141], s[40:41], 0, v[138:139]
	s_add_i32 m0, s45, 0xe000
	s_nop 0
	global_load_lds_dwordx4 v[140:141], off
	s_waitcnt vmcnt(8)
	s_waitcnt lgkmcnt(0)
	s_barrier
	s_nop 0
	s_waitcnt lgkmcnt(0)
	v_mfma_f32_16x16x32_bf16 v[126:129], v[146:149], v[178:181], v[126:129]
	v_mfma_f32_16x16x32_bf16 v[122:125], v[154:157], v[178:181], v[122:125]
	v_mfma_f32_16x16x32_bf16 v[118:121], v[146:149], v[186:189], v[118:121]
	v_mfma_f32_16x16x32_bf16 v[110:113], v[154:157], v[186:189], v[110:113]
	v_mfma_f32_16x16x32_bf16 v[102:105], v[146:149], v[194:197], v[102:105]
	v_mfma_f32_16x16x32_bf16 v[94:97], v[154:157], v[194:197], v[94:97]
	v_mfma_f32_16x16x32_bf16 v[86:89], v[146:149], v[202:205], v[86:89]
	v_mfma_f32_16x16x32_bf16 v[78:81], v[154:157], v[202:205], v[78:81]
	v_mfma_f32_16x16x32_bf16 v[126:129], v[150:153], v[182:185], v[126:129]
	v_mfma_f32_16x16x32_bf16 v[122:125], v[158:161], v[182:185], v[122:125]
	v_mfma_f32_16x16x32_bf16 v[118:121], v[150:153], v[190:193], v[118:121]
	v_mfma_f32_16x16x32_bf16 v[110:113], v[158:161], v[190:193], v[110:113]
	v_mfma_f32_16x16x32_bf16 v[102:105], v[150:153], v[198:201], v[102:105]
	v_mfma_f32_16x16x32_bf16 v[94:97], v[158:161], v[198:201], v[94:97]
	v_mfma_f32_16x16x32_bf16 v[86:89], v[150:153], v[224:227], v[86:89]
	v_mfma_f32_16x16x32_bf16 v[78:81], v[158:161], v[224:227], v[78:81]
	s_nop 0
	s_nop 0
	v_mfma_f32_16x16x32_bf16 v[114:117], v[162:165], v[178:181], v[114:117]
	v_mfma_f32_16x16x32_bf16 v[106:109], v[170:173], v[178:181], v[106:109]
	v_mfma_f32_16x16x32_bf16 v[98:101], v[162:165], v[186:189], v[98:101]
	v_mfma_f32_16x16x32_bf16 v[90:93], v[170:173], v[186:189], v[90:93]
	v_mfma_f32_16x16x32_bf16 v[82:85], v[162:165], v[194:197], v[82:85]
	v_mfma_f32_16x16x32_bf16 v[74:77], v[170:173], v[194:197], v[74:77]
	v_mfma_f32_16x16x32_bf16 v[70:73], v[162:165], v[202:205], v[70:73]
	v_mfma_f32_16x16x32_bf16 v[66:69], v[170:173], v[202:205], v[66:69]
	v_mfma_f32_16x16x32_bf16 v[114:117], v[166:169], v[182:185], v[114:117]
	v_mfma_f32_16x16x32_bf16 v[106:109], v[174:177], v[182:185], v[106:109]
	v_mfma_f32_16x16x32_bf16 v[98:101], v[166:169], v[190:193], v[98:101]
	v_mfma_f32_16x16x32_bf16 v[90:93], v[174:177], v[190:193], v[90:93]
	v_mfma_f32_16x16x32_bf16 v[82:85], v[166:169], v[198:201], v[82:85]
	v_mfma_f32_16x16x32_bf16 v[74:77], v[174:177], v[198:201], v[74:77]
	v_mfma_f32_16x16x32_bf16 v[70:73], v[166:169], v[224:227], v[70:73]
	v_mfma_f32_16x16x32_bf16 v[66:69], v[174:177], v[224:227], v[66:69]
	s_nop 0
	s_barrier
	s_add_i32 s88, s88, s37
	v_lshl_add_u64 v[140:141], s[28:29], 0, v[16:17]
	s_mov_b32 m0, s88
	ds_read_b128 v[178:181], v145 offset:16384
	ds_read_b128 v[182:185], v145 offset:17408
	ds_read_b128 v[186:189], v145 offset:18432
	ds_read_b128 v[190:193], v145 offset:19456
	ds_read_b128 v[194:197], v145 offset:20480
	ds_read_b128 v[198:201], v145 offset:21504
	ds_read_b128 v[202:205], v145 offset:22528
	ds_read_b128 v[224:227], v145 offset:23552
	global_load_lds_dwordx4 v[140:141], off
	s_add_i32 m0, s88, 0x2000
	s_add_u32 s88, s28, 0x20000
	v_lshl_add_u64 v[206:207], s[28:29], 0, v[130:131]
	s_addc_u32 s89, s29, 0
	s_add_i32 s90, s90, s37
	global_load_lds_dwordx4 v[206:207], off
	v_lshl_add_u64 v[228:229], s[88:89], 0, v[16:17]
	s_mov_b32 m0, s90
	v_lshl_add_u64 v[230:231], s[46:47], 0, v[132:133]
	global_load_lds_dwordx4 v[228:229], off
	v_lshl_add_u64 v[228:229], s[88:89], 0, v[130:131]
	s_add_i32 m0, s90, 0x2000
	s_nop 0
	global_load_lds_dwordx4 v[228:229], off
	v_lshl_add_u64 v[228:229], s[46:47], 0, v[134:135]
	s_mov_b32 m0, s45
	s_nop 0
	global_load_lds_dwordx4 v[228:229], off
	s_mov_b32 m0, s53
	s_nop 0
	global_load_lds_dwordx4 v[230:231], off
	s_waitcnt vmcnt(8)
	s_waitcnt lgkmcnt(0)
	s_barrier
	s_nop 0
	s_waitcnt lgkmcnt(0)
	v_mfma_f32_16x16x32_bf16 v[62:65], v[146:149], v[178:181], v[62:65]
	v_mfma_f32_16x16x32_bf16 v[58:61], v[154:157], v[178:181], v[58:61]
	v_mfma_f32_16x16x32_bf16 v[54:57], v[146:149], v[186:189], v[54:57]
	v_mfma_f32_16x16x32_bf16 v[46:49], v[154:157], v[186:189], v[46:49]
	v_mfma_f32_16x16x32_bf16 v[38:41], v[146:149], v[194:197], v[38:41]
	v_mfma_f32_16x16x32_bf16 v[30:33], v[154:157], v[194:197], v[30:33]
	v_mfma_f32_16x16x32_bf16 v[22:25], v[146:149], v[202:205], v[22:25]
	v_mfma_f32_16x16x32_bf16 v[12:15], v[154:157], v[202:205], v[12:15]
	v_mfma_f32_16x16x32_bf16 v[62:65], v[150:153], v[182:185], v[62:65]
	v_mfma_f32_16x16x32_bf16 v[58:61], v[158:161], v[182:185], v[58:61]
	v_mfma_f32_16x16x32_bf16 v[54:57], v[150:153], v[190:193], v[54:57]
	v_mfma_f32_16x16x32_bf16 v[46:49], v[158:161], v[190:193], v[46:49]
	v_mfma_f32_16x16x32_bf16 v[38:41], v[150:153], v[198:201], v[38:41]
	v_mfma_f32_16x16x32_bf16 v[30:33], v[158:161], v[198:201], v[30:33]
	v_mfma_f32_16x16x32_bf16 v[22:25], v[150:153], v[224:227], v[22:25]
	v_mfma_f32_16x16x32_bf16 v[12:15], v[158:161], v[224:227], v[12:15]
	s_nop 0
	s_nop 0
	v_mfma_f32_16x16x32_bf16 v[50:53], v[162:165], v[178:181], v[50:53]
	v_mfma_f32_16x16x32_bf16 v[42:45], v[170:173], v[178:181], v[42:45]
	v_mfma_f32_16x16x32_bf16 v[34:37], v[162:165], v[186:189], v[34:37]
	v_mfma_f32_16x16x32_bf16 v[26:29], v[170:173], v[186:189], v[26:29]
	v_mfma_f32_16x16x32_bf16 v[18:21], v[162:165], v[194:197], v[18:21]
	v_mfma_f32_16x16x32_bf16 v[8:11], v[170:173], v[194:197], v[8:11]
	v_mfma_f32_16x16x32_bf16 v[4:7], v[162:165], v[202:205], v[4:7]
	v_mfma_f32_16x16x32_bf16 v[0:3], v[170:173], v[202:205], v[0:3]
	v_mfma_f32_16x16x32_bf16 v[50:53], v[166:169], v[182:185], v[50:53]
	v_mfma_f32_16x16x32_bf16 v[42:45], v[174:177], v[182:185], v[42:45]
	v_mfma_f32_16x16x32_bf16 v[34:37], v[166:169], v[190:193], v[34:37]
	v_mfma_f32_16x16x32_bf16 v[26:29], v[174:177], v[190:193], v[26:29]
	v_mfma_f32_16x16x32_bf16 v[18:21], v[166:169], v[198:201], v[18:21]
	v_mfma_f32_16x16x32_bf16 v[8:11], v[174:177], v[198:201], v[8:11]
	v_mfma_f32_16x16x32_bf16 v[4:7], v[166:169], v[224:227], v[4:7]
	v_mfma_f32_16x16x32_bf16 v[0:3], v[174:177], v[224:227], v[0:3]
	s_nop 0
	s_barrier
	s_add_i32 s88, 0, 0x18000
	s_add_i32 s89, 0, 0x1c000
	v_add_u32_e32 v158, s88, v143
	v_add_u32_e32 v174, s89, v143
	ds_read_b128 v[146:149], v158
	ds_read_b128 v[150:153], v158 offset:1024
	ds_read_b128 v[154:157], v158 offset:2048
	ds_read_b128 v[158:161], v158 offset:3072
	ds_read_b128 v[162:165], v174
	ds_read_b128 v[166:169], v174 offset:1024
	ds_read_b128 v[170:173], v174 offset:2048
	ds_read_b128 v[174:177], v174 offset:3072
	s_add_u32 s46, s46, 0x80000
	s_addc_u32 s47, s47, 0
	s_mov_b32 m0, s58
	v_lshl_add_u64 v[232:233], s[46:47], 0, v[134:135]
	ds_read_b128 v[178:181], v145 offset:32768
	ds_read_b128 v[182:185], v145 offset:33792
	ds_read_b128 v[186:189], v145 offset:34816
	ds_read_b128 v[190:193], v145 offset:35840
	ds_read_b128 v[194:197], v145 offset:36864
	ds_read_b128 v[198:201], v145 offset:37888
	ds_read_b128 v[202:205], v145 offset:38912
	ds_read_b128 v[224:227], v145 offset:39936
	global_load_lds_dwordx4 v[232:233], off
	v_lshl_add_u64 v[232:233], s[46:47], 0, v[132:133]
	s_mov_b32 m0, s59
	s_nop 0
	global_load_lds_dwordx4 v[232:233], off
	s_waitcnt vmcnt(8)
	s_waitcnt lgkmcnt(0)
	s_barrier
	s_nop 0
	s_waitcnt lgkmcnt(0)
	v_mfma_f32_16x16x32_bf16 v[126:129], v[146:149], v[178:181], v[126:129]
	v_mfma_f32_16x16x32_bf16 v[122:125], v[154:157], v[178:181], v[122:125]
	v_mfma_f32_16x16x32_bf16 v[118:121], v[146:149], v[186:189], v[118:121]
	v_mfma_f32_16x16x32_bf16 v[110:113], v[154:157], v[186:189], v[110:113]
	v_mfma_f32_16x16x32_bf16 v[102:105], v[146:149], v[194:197], v[102:105]
	v_mfma_f32_16x16x32_bf16 v[94:97], v[154:157], v[194:197], v[94:97]
	v_mfma_f32_16x16x32_bf16 v[86:89], v[146:149], v[202:205], v[86:89]
	v_mfma_f32_16x16x32_bf16 v[78:81], v[154:157], v[202:205], v[78:81]
	v_mfma_f32_16x16x32_bf16 v[126:129], v[150:153], v[182:185], v[126:129]
	v_mfma_f32_16x16x32_bf16 v[122:125], v[158:161], v[182:185], v[122:125]
	v_mfma_f32_16x16x32_bf16 v[118:121], v[150:153], v[190:193], v[118:121]
	v_mfma_f32_16x16x32_bf16 v[110:113], v[158:161], v[190:193], v[110:113]
	v_mfma_f32_16x16x32_bf16 v[102:105], v[150:153], v[198:201], v[102:105]
	v_mfma_f32_16x16x32_bf16 v[94:97], v[158:161], v[198:201], v[94:97]
	v_mfma_f32_16x16x32_bf16 v[86:89], v[150:153], v[224:227], v[86:89]
	v_mfma_f32_16x16x32_bf16 v[78:81], v[158:161], v[224:227], v[78:81]
	s_nop 0
	s_nop 0
	v_mfma_f32_16x16x32_bf16 v[114:117], v[162:165], v[178:181], v[114:117]
	v_mfma_f32_16x16x32_bf16 v[106:109], v[170:173], v[178:181], v[106:109]
	v_mfma_f32_16x16x32_bf16 v[98:101], v[162:165], v[186:189], v[98:101]
	v_mfma_f32_16x16x32_bf16 v[90:93], v[170:173], v[186:189], v[90:93]
	v_mfma_f32_16x16x32_bf16 v[82:85], v[162:165], v[194:197], v[82:85]
	v_mfma_f32_16x16x32_bf16 v[74:77], v[170:173], v[194:197], v[74:77]
	v_mfma_f32_16x16x32_bf16 v[70:73], v[162:165], v[202:205], v[70:73]
	v_mfma_f32_16x16x32_bf16 v[66:69], v[170:173], v[202:205], v[66:69]
	v_mfma_f32_16x16x32_bf16 v[114:117], v[166:169], v[182:185], v[114:117]
	v_mfma_f32_16x16x32_bf16 v[106:109], v[174:177], v[182:185], v[106:109]
	v_mfma_f32_16x16x32_bf16 v[98:101], v[166:169], v[190:193], v[98:101]
	v_mfma_f32_16x16x32_bf16 v[90:93], v[174:177], v[190:193], v[90:93]
	v_mfma_f32_16x16x32_bf16 v[82:85], v[166:169], v[198:201], v[82:85]
	v_mfma_f32_16x16x32_bf16 v[74:77], v[174:177], v[198:201], v[74:77]
	v_mfma_f32_16x16x32_bf16 v[70:73], v[166:169], v[224:227], v[70:73]
	v_mfma_f32_16x16x32_bf16 v[66:69], v[174:177], v[224:227], v[66:69]
	s_nop 0
	s_barrier
	s_add_i32 s46, s88, s37
	v_lshl_add_u64 v[140:141], v[140:141], 0, s[34:35]
	s_mov_b32 m0, s46
	ds_read_b128 v[178:181], v145 offset:49152
	ds_read_b128 v[182:185], v145 offset:50176
	ds_read_b128 v[186:189], v145 offset:51200
	ds_read_b128 v[190:193], v145 offset:52224
	ds_read_b128 v[194:197], v145 offset:53248
	ds_read_b128 v[198:201], v145 offset:54272
	ds_read_b128 v[202:205], v145 offset:55296
	ds_read_b128 v[224:227], v145 offset:56320
	global_load_lds_dwordx4 v[140:141], off
	s_add_i32 m0, s46, 0x2000
	s_add_u32 s28, s28, 0x20080
	v_lshl_add_u64 v[140:141], v[206:207], 0, s[34:35]
	s_addc_u32 s29, s29, 0
	s_add_i32 s46, s89, s37
	global_load_lds_dwordx4 v[140:141], off
	v_lshl_add_u64 v[140:141], s[28:29], 0, v[16:17]
	s_mov_b32 m0, s46
	s_nop 0
	global_load_lds_dwordx4 v[140:141], off
	v_lshl_add_u64 v[140:141], s[28:29], 0, v[130:131]
	s_add_i32 m0, s46, 0x2000
	s_nop 0
	global_load_lds_dwordx4 v[140:141], off
	v_lshl_add_u64 v[140:141], v[228:229], 0, s[34:35]
	s_mov_b32 m0, s83
	s_nop 0
	global_load_lds_dwordx4 v[140:141], off
	v_lshl_add_u64 v[140:141], v[230:231], 0, s[34:35]
	s_mov_b32 m0, s84
	s_nop 0
	global_load_lds_dwordx4 v[140:141], off
	s_waitcnt vmcnt(8)
	s_waitcnt lgkmcnt(0)
	s_barrier
	s_nop 0
	s_waitcnt lgkmcnt(0)
	v_mfma_f32_16x16x32_bf16 v[62:65], v[146:149], v[178:181], v[62:65]
	v_mfma_f32_16x16x32_bf16 v[58:61], v[154:157], v[178:181], v[58:61]
	v_mfma_f32_16x16x32_bf16 v[54:57], v[146:149], v[186:189], v[54:57]
	v_mfma_f32_16x16x32_bf16 v[46:49], v[154:157], v[186:189], v[46:49]
	v_mfma_f32_16x16x32_bf16 v[38:41], v[146:149], v[194:197], v[38:41]
	v_mfma_f32_16x16x32_bf16 v[30:33], v[154:157], v[194:197], v[30:33]
	v_mfma_f32_16x16x32_bf16 v[22:25], v[146:149], v[202:205], v[22:25]
	v_mfma_f32_16x16x32_bf16 v[12:15], v[154:157], v[202:205], v[12:15]
	v_mfma_f32_16x16x32_bf16 v[62:65], v[150:153], v[182:185], v[62:65]
	v_mfma_f32_16x16x32_bf16 v[58:61], v[158:161], v[182:185], v[58:61]
	v_mfma_f32_16x16x32_bf16 v[54:57], v[150:153], v[190:193], v[54:57]
	v_mfma_f32_16x16x32_bf16 v[46:49], v[158:161], v[190:193], v[46:49]
	v_mfma_f32_16x16x32_bf16 v[38:41], v[150:153], v[198:201], v[38:41]
	v_mfma_f32_16x16x32_bf16 v[30:33], v[158:161], v[198:201], v[30:33]
	v_mfma_f32_16x16x32_bf16 v[22:25], v[150:153], v[224:227], v[22:25]
	v_mfma_f32_16x16x32_bf16 v[12:15], v[158:161], v[224:227], v[12:15]
	s_nop 0
	s_nop 0
	v_mfma_f32_16x16x32_bf16 v[50:53], v[162:165], v[178:181], v[50:53]
	v_mfma_f32_16x16x32_bf16 v[42:45], v[170:173], v[178:181], v[42:45]
	v_mfma_f32_16x16x32_bf16 v[34:37], v[162:165], v[186:189], v[34:37]
	v_mfma_f32_16x16x32_bf16 v[26:29], v[170:173], v[186:189], v[26:29]
	v_mfma_f32_16x16x32_bf16 v[18:21], v[162:165], v[194:197], v[18:21]
	v_mfma_f32_16x16x32_bf16 v[8:11], v[170:173], v[194:197], v[8:11]
	v_mfma_f32_16x16x32_bf16 v[4:7], v[162:165], v[202:205], v[4:7]
	v_mfma_f32_16x16x32_bf16 v[0:3], v[170:173], v[202:205], v[0:3]
	v_mfma_f32_16x16x32_bf16 v[50:53], v[166:169], v[182:185], v[50:53]
	v_mfma_f32_16x16x32_bf16 v[42:45], v[174:177], v[182:185], v[42:45]
	v_mfma_f32_16x16x32_bf16 v[34:37], v[166:169], v[190:193], v[34:37]
	v_mfma_f32_16x16x32_bf16 v[26:29], v[174:177], v[190:193], v[26:29]
	v_mfma_f32_16x16x32_bf16 v[18:21], v[166:169], v[198:201], v[18:21]
	v_mfma_f32_16x16x32_bf16 v[8:11], v[174:177], v[198:201], v[8:11]
	v_mfma_f32_16x16x32_bf16 v[4:7], v[166:169], v[224:227], v[4:7]
	v_mfma_f32_16x16x32_bf16 v[0:3], v[174:177], v[224:227], v[0:3]
	s_nop 0
	s_barrier
	s_add_i32 s87, s87, 2
	s_add_u32 s40, s40, 0x100
	s_addc_u32 s41, s41, 0
	s_add_u32 s48, s48, 0x100
	s_addc_u32 s49, s49, 0
	s_cmp_gt_u32 s87, 5
	s_cbranch_scc0 .LBB0_649
	s_and_b64 vcc, exec, s[14:15]
	s_cbranch_vccz .LBB0_652
	s_barrier

.LBB0_655:
	s_setprio 0
	s_waitcnt vmcnt(0)
	s_barrier

.LBB0_717:
	s_add_u32 s28, s44, 0xfff80080
	s_addc_u32 s29, s45, -1
	s_add_i32 s89, 0, 0x10000
	s_cmp_eq_u32 s88, 28
	s_cselect_b32 s47, s23, s29
	s_cselect_b32 s46, s84, s28
	s_cselect_b32 s29, s19, s87
	s_cselect_b32 s28, s85, s86
	s_add_i32 s92, 0, 0x14000
	v_add_u32_e32 v148, s89, v224
	v_add_u32_e32 v164, s92, v224
	ds_read_b128 v[136:139], v148
	ds_read_b128 v[140:143], v148 offset:1024
	ds_read_b128 v[144:147], v148 offset:2048
	ds_read_b128 v[148:151], v148 offset:3072
	ds_read_b128 v[152:155], v164
	ds_read_b128 v[156:159], v164 offset:1024
	ds_read_b128 v[160:163], v164 offset:2048
	ds_read_b128 v[164:167], v164 offset:3072
	v_lshl_add_u64 v[200:201], s[44:45], 0, v[132:133]
	s_add_i32 m0, s43, 0xc000
	ds_read_b128 v[168:171], v226
	ds_read_b128 v[172:175], v226 offset:1024
	ds_read_b128 v[176:179], v226 offset:2048
	ds_read_b128 v[180:183], v226 offset:3072
	ds_read_b128 v[184:187], v226 offset:4096
	ds_read_b128 v[188:191], v226 offset:5120
	ds_read_b128 v[192:195], v226 offset:6144
	ds_read_b128 v[196:199], v226 offset:7168
	global_load_lds_dwordx4 v[200:201], off
	v_lshl_add_u64 v[200:201], s[44:45], 0, v[134:135]
	s_add_i32 m0, s43, 0xe000
	s_nop 0
	global_load_lds_dwordx4 v[200:201], off
	s_waitcnt vmcnt(8)
	s_waitcnt lgkmcnt(0)
	s_barrier
	s_nop 0
	s_waitcnt lgkmcnt(0)
	v_mfma_f32_16x16x32_bf16 v[126:129], v[136:139], v[168:171], v[126:129]
	v_mfma_f32_16x16x32_bf16 v[122:125], v[144:147], v[168:171], v[122:125]
	v_mfma_f32_16x16x32_bf16 v[118:121], v[136:139], v[176:179], v[118:121]
	v_mfma_f32_16x16x32_bf16 v[114:117], v[144:147], v[176:179], v[114:117]
	v_mfma_f32_16x16x32_bf16 v[110:113], v[136:139], v[184:187], v[110:113]
	v_mfma_f32_16x16x32_bf16 v[106:109], v[144:147], v[184:187], v[106:109]
	v_mfma_f32_16x16x32_bf16 v[102:105], v[136:139], v[192:195], v[102:105]
	v_mfma_f32_16x16x32_bf16 v[98:101], v[144:147], v[192:195], v[98:101]
	v_mfma_f32_16x16x32_bf16 v[126:129], v[140:143], v[172:175], v[126:129]
	v_mfma_f32_16x16x32_bf16 v[122:125], v[148:151], v[172:175], v[122:125]
	v_mfma_f32_16x16x32_bf16 v[118:121], v[140:143], v[180:183], v[118:121]
	v_mfma_f32_16x16x32_bf16 v[114:117], v[148:151], v[180:183], v[114:117]
	v_mfma_f32_16x16x32_bf16 v[110:113], v[140:143], v[188:191], v[110:113]
	v_mfma_f32_16x16x32_bf16 v[106:109], v[148:151], v[188:191], v[106:109]
	v_mfma_f32_16x16x32_bf16 v[102:105], v[140:143], v[196:199], v[102:105]
	v_mfma_f32_16x16x32_bf16 v[98:101], v[148:151], v[196:199], v[98:101]
	s_nop 0
	s_nop 0
	v_mfma_f32_16x16x32_bf16 v[94:97], v[152:155], v[168:171], v[94:97]
	v_mfma_f32_16x16x32_bf16 v[90:93], v[160:163], v[168:171], v[90:93]
	v_mfma_f32_16x16x32_bf16 v[86:89], v[152:155], v[176:179], v[86:89]
	v_mfma_f32_16x16x32_bf16 v[82:85], v[160:163], v[176:179], v[82:85]
	v_mfma_f32_16x16x32_bf16 v[78:81], v[152:155], v[184:187], v[78:81]
	v_mfma_f32_16x16x32_bf16 v[74:77], v[160:163], v[184:187], v[74:77]
	v_mfma_f32_16x16x32_bf16 v[70:73], v[152:155], v[192:195], v[70:73]
	v_mfma_f32_16x16x32_bf16 v[66:69], v[160:163], v[192:195], v[66:69]
	v_mfma_f32_16x16x32_bf16 v[94:97], v[156:159], v[172:175], v[94:97]
	v_mfma_f32_16x16x32_bf16 v[90:93], v[164:167], v[172:175], v[90:93]
	v_mfma_f32_16x16x32_bf16 v[86:89], v[156:159], v[180:183], v[86:89]
	v_mfma_f32_16x16x32_bf16 v[82:85], v[164:167], v[180:183], v[82:85]
	v_mfma_f32_16x16x32_bf16 v[78:81], v[156:159], v[188:191], v[78:81]
	v_mfma_f32_16x16x32_bf16 v[74:77], v[164:167], v[188:191], v[74:77]
	v_mfma_f32_16x16x32_bf16 v[70:73], v[156:159], v[196:199], v[70:73]
	v_mfma_f32_16x16x32_bf16 v[66:69], v[164:167], v[196:199], v[66:69]
	s_nop 0
	s_barrier
	s_add_i32 s89, s89, s37
	v_lshl_add_u64 v[200:201], s[28:29], 0, v[16:17]
	s_mov_b32 m0, s89
	ds_read_b128 v[168:171], v226 offset:16384
	ds_read_b128 v[172:175], v226 offset:17408
	ds_read_b128 v[176:179], v226 offset:18432
	ds_read_b128 v[180:183], v226 offset:19456
	ds_read_b128 v[184:187], v226 offset:20480
	ds_read_b128 v[188:191], v226 offset:21504
	ds_read_b128 v[192:195], v226 offset:22528
	ds_read_b128 v[196:199], v226 offset:23552
	global_load_lds_dwordx4 v[200:201], off
	s_add_i32 m0, s89, 0x2000
	s_add_u32 s90, s28, 0x80000
	v_lshl_add_u64 v[202:203], s[28:29], 0, v[130:131]
	s_addc_u32 s91, s29, 0
	s_add_i32 s89, s92, s37
	global_load_lds_dwordx4 v[202:203], off
	v_lshl_add_u64 v[204:205], s[90:91], 0, v[16:17]
	s_mov_b32 m0, s89
	v_lshl_add_u64 v[206:207], s[46:47], 0, v[130:131]
	global_load_lds_dwordx4 v[204:205], off
	v_lshl_add_u64 v[204:205], s[90:91], 0, v[130:131]
	s_add_i32 m0, s89, 0x2000
	s_nop 0
	global_load_lds_dwordx4 v[204:205], off
	v_lshl_add_u64 v[204:205], s[46:47], 0, v[16:17]
	s_mov_b32 m0, s43
	s_nop 0
	global_load_lds_dwordx4 v[204:205], off
	s_mov_b32 m0, s50
	s_nop 0
	global_load_lds_dwordx4 v[206:207], off
	s_waitcnt vmcnt(8)
	s_waitcnt lgkmcnt(0)
	s_barrier
	s_nop 0
	s_waitcnt lgkmcnt(0)
	v_mfma_f32_16x16x32_bf16 v[62:65], v[136:139], v[168:171], v[62:65]
	v_mfma_f32_16x16x32_bf16 v[58:61], v[144:147], v[168:171], v[58:61]
	v_mfma_f32_16x16x32_bf16 v[54:57], v[136:139], v[176:179], v[54:57]
	v_mfma_f32_16x16x32_bf16 v[50:53], v[144:147], v[176:179], v[50:53]
	v_mfma_f32_16x16x32_bf16 v[46:49], v[136:139], v[184:187], v[46:49]
	v_mfma_f32_16x16x32_bf16 v[42:45], v[144:147], v[184:187], v[42:45]
	v_mfma_f32_16x16x32_bf16 v[38:41], v[136:139], v[192:195], v[38:41]
	v_mfma_f32_16x16x32_bf16 v[34:37], v[144:147], v[192:195], v[34:37]
	v_mfma_f32_16x16x32_bf16 v[62:65], v[140:143], v[172:175], v[62:65]
	v_mfma_f32_16x16x32_bf16 v[58:61], v[148:151], v[172:175], v[58:61]
	v_mfma_f32_16x16x32_bf16 v[54:57], v[140:143], v[180:183], v[54:57]
	v_mfma_f32_16x16x32_bf16 v[50:53], v[148:151], v[180:183], v[50:53]
	v_mfma_f32_16x16x32_bf16 v[46:49], v[140:143], v[188:191], v[46:49]
	v_mfma_f32_16x16x32_bf16 v[42:45], v[148:151], v[188:191], v[42:45]
	v_mfma_f32_16x16x32_bf16 v[38:41], v[140:143], v[196:199], v[38:41]
	v_mfma_f32_16x16x32_bf16 v[34:37], v[148:151], v[196:199], v[34:37]
	s_nop 0
	s_nop 0
	v_mfma_f32_16x16x32_bf16 v[30:33], v[152:155], v[168:171], v[30:33]
	v_mfma_f32_16x16x32_bf16 v[26:29], v[160:163], v[168:171], v[26:29]
	v_mfma_f32_16x16x32_bf16 v[22:25], v[152:155], v[176:179], v[22:25]
	v_mfma_f32_16x16x32_bf16 v[18:21], v[160:163], v[176:179], v[18:21]
	v_mfma_f32_16x16x32_bf16 v[12:15], v[152:155], v[184:187], v[12:15]
	v_mfma_f32_16x16x32_bf16 v[8:11], v[160:163], v[184:187], v[8:11]
	v_mfma_f32_16x16x32_bf16 v[4:7], v[152:155], v[192:195], v[4:7]
	v_mfma_f32_16x16x32_bf16 v[0:3], v[160:163], v[192:195], v[0:3]
	v_mfma_f32_16x16x32_bf16 v[30:33], v[156:159], v[172:175], v[30:33]
	v_mfma_f32_16x16x32_bf16 v[26:29], v[164:167], v[172:175], v[26:29]
	v_mfma_f32_16x16x32_bf16 v[22:25], v[156:159], v[180:183], v[22:25]
	v_mfma_f32_16x16x32_bf16 v[18:21], v[164:167], v[180:183], v[18:21]
	v_mfma_f32_16x16x32_bf16 v[12:15], v[156:159], v[188:191], v[12:15]
	v_mfma_f32_16x16x32_bf16 v[8:11], v[164:167], v[188:191], v[8:11]
	v_mfma_f32_16x16x32_bf16 v[4:7], v[156:159], v[196:199], v[4:7]
	v_mfma_f32_16x16x32_bf16 v[0:3], v[164:167], v[196:199], v[0:3]
	s_nop 0
	s_barrier
	s_add_i32 s89, 0, 0x18000
	s_add_i32 s90, 0, 0x1c000
	v_add_u32_e32 v148, s89, v224
	v_add_u32_e32 v164, s90, v224
	ds_read_b128 v[136:139], v148
	ds_read_b128 v[140:143], v148 offset:1024
	ds_read_b128 v[144:147], v148 offset:2048
	ds_read_b128 v[148:151], v148 offset:3072
	ds_read_b128 v[152:155], v164
	ds_read_b128 v[156:159], v164 offset:1024
	ds_read_b128 v[160:163], v164 offset:2048
	ds_read_b128 v[164:167], v164 offset:3072
	s_add_u32 s46, s46, 0x80000
	s_addc_u32 s47, s47, 0
	s_mov_b32 m0, s51
	v_lshl_add_u64 v[228:229], s[46:47], 0, v[16:17]
	ds_read_b128 v[168:171], v226 offset:32768
	ds_read_b128 v[172:175], v226 offset:33792
	ds_read_b128 v[176:179], v226 offset:34816
	ds_read_b128 v[180:183], v226 offset:35840
	ds_read_b128 v[184:187], v226 offset:36864
	ds_read_b128 v[188:191], v226 offset:37888
	ds_read_b128 v[192:195], v226 offset:38912
	ds_read_b128 v[196:199], v226 offset:39936
	global_load_lds_dwordx4 v[228:229], off
	v_lshl_add_u64 v[228:229], s[46:47], 0, v[130:131]
	s_mov_b32 m0, s52
	s_nop 0
	global_load_lds_dwordx4 v[228:229], off
	s_waitcnt vmcnt(8)
	s_waitcnt lgkmcnt(0)
	s_barrier
	s_nop 0
	s_waitcnt lgkmcnt(0)
	v_mfma_f32_16x16x32_bf16 v[126:129], v[136:139], v[168:171], v[126:129]
	v_mfma_f32_16x16x32_bf16 v[122:125], v[144:147], v[168:171], v[122:125]
	v_mfma_f32_16x16x32_bf16 v[118:121], v[136:139], v[176:179], v[118:121]
	v_mfma_f32_16x16x32_bf16 v[114:117], v[144:147], v[176:179], v[114:117]
	v_mfma_f32_16x16x32_bf16 v[110:113], v[136:139], v[184:187], v[110:113]
	v_mfma_f32_16x16x32_bf16 v[106:109], v[144:147], v[184:187], v[106:109]
	v_mfma_f32_16x16x32_bf16 v[102:105], v[136:139], v[192:195], v[102:105]
	v_mfma_f32_16x16x32_bf16 v[98:101], v[144:147], v[192:195], v[98:101]
	v_mfma_f32_16x16x32_bf16 v[126:129], v[140:143], v[172:175], v[126:129]
	v_mfma_f32_16x16x32_bf16 v[122:125], v[148:151], v[172:175], v[122:125]
	v_mfma_f32_16x16x32_bf16 v[118:121], v[140:143], v[180:183], v[118:121]
	v_mfma_f32_16x16x32_bf16 v[114:117], v[148:151], v[180:183], v[114:117]
	v_mfma_f32_16x16x32_bf16 v[110:113], v[140:143], v[188:191], v[110:113]
	v_mfma_f32_16x16x32_bf16 v[106:109], v[148:151], v[188:191], v[106:109]
	v_mfma_f32_16x16x32_bf16 v[102:105], v[140:143], v[196:199], v[102:105]
	v_mfma_f32_16x16x32_bf16 v[98:101], v[148:151], v[196:199], v[98:101]
	s_nop 0
	s_nop 0
	v_mfma_f32_16x16x32_bf16 v[94:97], v[152:155], v[168:171], v[94:97]
	v_mfma_f32_16x16x32_bf16 v[90:93], v[160:163], v[168:171], v[90:93]
	v_mfma_f32_16x16x32_bf16 v[86:89], v[152:155], v[176:179], v[86:89]
	v_mfma_f32_16x16x32_bf16 v[82:85], v[160:163], v[176:179], v[82:85]
	v_mfma_f32_16x16x32_bf16 v[78:81], v[152:155], v[184:187], v[78:81]
	v_mfma_f32_16x16x32_bf16 v[74:77], v[160:163], v[184:187], v[74:77]
	v_mfma_f32_16x16x32_bf16 v[70:73], v[152:155], v[192:195], v[70:73]
	v_mfma_f32_16x16x32_bf16 v[66:69], v[160:163], v[192:195], v[66:69]
	v_mfma_f32_16x16x32_bf16 v[94:97], v[156:159], v[172:175], v[94:97]
	v_mfma_f32_16x16x32_bf16 v[90:93], v[164:167], v[172:175], v[90:93]
	v_mfma_f32_16x16x32_bf16 v[86:89], v[156:159], v[180:183], v[86:89]
	v_mfma_f32_16x16x32_bf16 v[82:85], v[164:167], v[180:183], v[82:85]
	v_mfma_f32_16x16x32_bf16 v[78:81], v[156:159], v[188:191], v[78:81]
	v_mfma_f32_16x16x32_bf16 v[74:77], v[164:167], v[188:191], v[74:77]
	v_mfma_f32_16x16x32_bf16 v[70:73], v[156:159], v[196:199], v[70:73]
	v_mfma_f32_16x16x32_bf16 v[66:69], v[164:167], v[196:199], v[66:69]
	s_nop 0
	s_barrier
	s_add_i32 s46, s89, s37
	v_lshl_add_u64 v[200:201], v[200:201], 0, s[34:35]
	s_mov_b32 m0, s46
	ds_read_b128 v[168:171], v226 offset:49152
	ds_read_b128 v[172:175], v226 offset:50176
	ds_read_b128 v[176:179], v226 offset:51200
	ds_read_b128 v[180:183], v226 offset:52224
	ds_read_b128 v[184:187], v226 offset:53248
	ds_read_b128 v[188:191], v226 offset:54272
	ds_read_b128 v[192:195], v226 offset:55296
	ds_read_b128 v[196:199], v226 offset:56320
	global_load_lds_dwordx4 v[200:201], off
	s_add_i32 m0, s46, 0x2000
	s_add_u32 s28, s28, 0x80080
	v_lshl_add_u64 v[200:201], v[202:203], 0, s[34:35]
	s_addc_u32 s29, s29, 0
	s_add_i32 s46, s90, s37
	global_load_lds_dwordx4 v[200:201], off
	v_lshl_add_u64 v[200:201], s[28:29], 0, v[16:17]
	s_mov_b32 m0, s46
	s_nop 0
	global_load_lds_dwordx4 v[200:201], off
	v_lshl_add_u64 v[200:201], s[28:29], 0, v[130:131]
	s_add_i32 m0, s46, 0x2000
	s_nop 0
	global_load_lds_dwordx4 v[200:201], off
	v_lshl_add_u64 v[200:201], v[204:205], 0, s[34:35]
	s_mov_b32 m0, s53
	s_nop 0
	global_load_lds_dwordx4 v[200:201], off
	v_lshl_add_u64 v[200:201], v[206:207], 0, s[34:35]
	s_mov_b32 m0, s58
	s_nop 0
	global_load_lds_dwordx4 v[200:201], off
	s_waitcnt vmcnt(8)
	s_waitcnt lgkmcnt(0)
	s_barrier
	s_nop 0
	s_waitcnt lgkmcnt(0)
	v_mfma_f32_16x16x32_bf16 v[62:65], v[136:139], v[168:171], v[62:65]
	v_mfma_f32_16x16x32_bf16 v[58:61], v[144:147], v[168:171], v[58:61]
	v_mfma_f32_16x16x32_bf16 v[54:57], v[136:139], v[176:179], v[54:57]
	v_mfma_f32_16x16x32_bf16 v[50:53], v[144:147], v[176:179], v[50:53]
	v_mfma_f32_16x16x32_bf16 v[46:49], v[136:139], v[184:187], v[46:49]
	v_mfma_f32_16x16x32_bf16 v[42:45], v[144:147], v[184:187], v[42:45]
	v_mfma_f32_16x16x32_bf16 v[38:41], v[136:139], v[192:195], v[38:41]
	v_mfma_f32_16x16x32_bf16 v[34:37], v[144:147], v[192:195], v[34:37]
	v_mfma_f32_16x16x32_bf16 v[62:65], v[140:143], v[172:175], v[62:65]
	v_mfma_f32_16x16x32_bf16 v[58:61], v[148:151], v[172:175], v[58:61]
	v_mfma_f32_16x16x32_bf16 v[54:57], v[140:143], v[180:183], v[54:57]
	v_mfma_f32_16x16x32_bf16 v[50:53], v[148:151], v[180:183], v[50:53]
	v_mfma_f32_16x16x32_bf16 v[46:49], v[140:143], v[188:191], v[46:49]
	v_mfma_f32_16x16x32_bf16 v[42:45], v[148:151], v[188:191], v[42:45]
	v_mfma_f32_16x16x32_bf16 v[38:41], v[140:143], v[196:199], v[38:41]
	v_mfma_f32_16x16x32_bf16 v[34:37], v[148:151], v[196:199], v[34:37]
	s_nop 0
	s_nop 0
	v_mfma_f32_16x16x32_bf16 v[30:33], v[152:155], v[168:171], v[30:33]
	v_mfma_f32_16x16x32_bf16 v[26:29], v[160:163], v[168:171], v[26:29]
	v_mfma_f32_16x16x32_bf16 v[22:25], v[152:155], v[176:179], v[22:25]
	v_mfma_f32_16x16x32_bf16 v[18:21], v[160:163], v[176:179], v[18:21]
	v_mfma_f32_16x16x32_bf16 v[12:15], v[152:155], v[184:187], v[12:15]
	v_mfma_f32_16x16x32_bf16 v[8:11], v[160:163], v[184:187], v[8:11]
	v_mfma_f32_16x16x32_bf16 v[4:7], v[152:155], v[192:195], v[4:7]
	v_mfma_f32_16x16x32_bf16 v[0:3], v[160:163], v[192:195], v[0:3]
	v_mfma_f32_16x16x32_bf16 v[30:33], v[156:159], v[172:175], v[30:33]
	v_mfma_f32_16x16x32_bf16 v[26:29], v[164:167], v[172:175], v[26:29]
	v_mfma_f32_16x16x32_bf16 v[22:25], v[156:159], v[180:183], v[22:25]
	v_mfma_f32_16x16x32_bf16 v[18:21], v[164:167], v[180:183], v[18:21]
	v_mfma_f32_16x16x32_bf16 v[12:15], v[156:159], v[188:191], v[12:15]
	v_mfma_f32_16x16x32_bf16 v[8:11], v[164:167], v[188:191], v[8:11]
	v_mfma_f32_16x16x32_bf16 v[4:7], v[156:159], v[196:199], v[4:7]
	v_mfma_f32_16x16x32_bf16 v[0:3], v[164:167], v[196:199], v[0:3]
	s_nop 0
	s_barrier
	s_add_i32 s88, s88, 2
	s_add_u32 s44, s44, 0x100
	s_addc_u32 s45, s45, 0
	s_add_u32 s86, s86, 0x100
	s_addc_u32 s87, s87, 0
	s_cmp_gt_u32 s88, 29
	s_cbranch_scc0 .LBB0_717
	s_and_b64 vcc, exec, s[14:15]
	s_cbranch_vccz .LBB0_720
	s_barrier

.LBB0_784:
	s_and_b64 vcc, exec, s[18:19]
	s_cbranch_vccz .Lsp_G
	s_setprio 1

.LBB0_787:
	s_add_u32 s28, s50, 0xfff80080
	s_addc_u32 s29, s51, -1
	s_add_i32 s94, 0, 0x10000
	s_cmp_eq_u32 s93, 28
	s_cselect_b32 s53, s43, s29
	s_cselect_b32 s52, s91, s28
	s_cselect_b32 s29, s41, s92
	s_cselect_b32 s28, vcc_lo, vcc_hi
	s_add_i32 s96, 0, 0x14000
	s_waitcnt vmcnt(0)
	v_add_u32_e32 v142, s94, v207
	v_add_u32_e32 v158, s96, v207
	ds_read_b128 v[130:133], v142
	ds_read_b128 v[134:137], v142 offset:1024
	ds_read_b128 v[138:141], v142 offset:2048
	ds_read_b128 v[142:145], v142 offset:3072
	ds_read_b128 v[146:149], v158
	ds_read_b128 v[150:153], v158 offset:1024
	ds_read_b128 v[154:157], v158 offset:2048
	ds_read_b128 v[158:161], v158 offset:3072
	v_lshl_add_u64 v[204:205], s[50:51], 0, v[192:193]
	s_add_i32 m0, s59, 0xc000
	ds_read_b128 v[162:165], v224
	ds_read_b128 v[166:169], v224 offset:1024
	ds_read_b128 v[170:173], v224 offset:2048
	ds_read_b128 v[174:177], v224 offset:3072
	ds_read_b128 v[178:181], v224 offset:4096
	ds_read_b128 v[182:185], v224 offset:5120
	ds_read_b128 v[196:199], v224 offset:6144
	ds_read_b128 v[200:203], v224 offset:7168
	global_load_lds_dwordx4 v[204:205], off
	v_lshl_add_u64 v[204:205], s[50:51], 0, v[194:195]
	s_add_i32 m0, s59, 0xe000
	s_nop 0
	global_load_lds_dwordx4 v[204:205], off
	s_waitcnt vmcnt(8)
	s_waitcnt lgkmcnt(0)
	s_barrier
	s_nop 0
	s_waitcnt lgkmcnt(0)
	v_mfma_f32_16x16x32_bf16 v[126:129], v[130:133], v[162:165], v[126:129]
	v_mfma_f32_16x16x32_bf16 v[122:125], v[138:141], v[162:165], v[122:125]
	v_mfma_f32_16x16x32_bf16 v[114:117], v[130:133], v[170:173], v[114:117]
	v_mfma_f32_16x16x32_bf16 v[106:109], v[138:141], v[170:173], v[106:109]
	v_mfma_f32_16x16x32_bf16 v[98:101], v[130:133], v[178:181], v[98:101]
	v_mfma_f32_16x16x32_bf16 v[90:93], v[138:141], v[178:181], v[90:93]
	v_mfma_f32_16x16x32_bf16 v[82:85], v[130:133], v[196:199], v[82:85]
	v_mfma_f32_16x16x32_bf16 v[74:77], v[138:141], v[196:199], v[74:77]
	v_mfma_f32_16x16x32_bf16 v[126:129], v[134:137], v[166:169], v[126:129]
	v_mfma_f32_16x16x32_bf16 v[122:125], v[142:145], v[166:169], v[122:125]
	v_mfma_f32_16x16x32_bf16 v[114:117], v[134:137], v[174:177], v[114:117]
	v_mfma_f32_16x16x32_bf16 v[106:109], v[142:145], v[174:177], v[106:109]
	v_mfma_f32_16x16x32_bf16 v[98:101], v[134:137], v[182:185], v[98:101]
	v_mfma_f32_16x16x32_bf16 v[90:93], v[142:145], v[182:185], v[90:93]
	v_mfma_f32_16x16x32_bf16 v[82:85], v[134:137], v[200:203], v[82:85]
	v_mfma_f32_16x16x32_bf16 v[74:77], v[142:145], v[200:203], v[74:77]
	s_nop 0
	s_nop 0
	v_mfma_f32_16x16x32_bf16 v[118:121], v[146:149], v[162:165], v[118:121]
	v_mfma_f32_16x16x32_bf16 v[110:113], v[154:157], v[162:165], v[110:113]
	v_mfma_f32_16x16x32_bf16 v[102:105], v[146:149], v[170:173], v[102:105]
	v_mfma_f32_16x16x32_bf16 v[94:97], v[154:157], v[170:173], v[94:97]
	v_mfma_f32_16x16x32_bf16 v[86:89], v[146:149], v[178:181], v[86:89]
	v_mfma_f32_16x16x32_bf16 v[78:81], v[154:157], v[178:181], v[78:81]
	v_mfma_f32_16x16x32_bf16 v[70:73], v[146:149], v[196:199], v[70:73]
	v_mfma_f32_16x16x32_bf16 v[66:69], v[154:157], v[196:199], v[66:69]
	v_mfma_f32_16x16x32_bf16 v[118:121], v[150:153], v[166:169], v[118:121]
	v_mfma_f32_16x16x32_bf16 v[110:113], v[158:161], v[166:169], v[110:113]
	v_mfma_f32_16x16x32_bf16 v[102:105], v[150:153], v[174:177], v[102:105]
	v_mfma_f32_16x16x32_bf16 v[94:97], v[158:161], v[174:177], v[94:97]
	v_mfma_f32_16x16x32_bf16 v[86:89], v[150:153], v[182:185], v[86:89]
	v_mfma_f32_16x16x32_bf16 v[78:81], v[158:161], v[182:185], v[78:81]
	v_mfma_f32_16x16x32_bf16 v[70:73], v[150:153], v[200:203], v[70:73]
	v_mfma_f32_16x16x32_bf16 v[66:69], v[158:161], v[200:203], v[66:69]
	s_nop 0
	s_barrier
	s_add_i32 s94, s94, s37
	v_lshl_add_u64 v[204:205], s[28:29], 0, v[16:17]
	s_mov_b32 m0, s94
	ds_read_b128 v[162:165], v224 offset:16384
	ds_read_b128 v[166:169], v224 offset:17408
	ds_read_b128 v[170:173], v224 offset:18432
	ds_read_b128 v[174:177], v224 offset:19456
	ds_read_b128 v[178:181], v224 offset:20480
	ds_read_b128 v[182:185], v224 offset:21504
	ds_read_b128 v[196:199], v224 offset:22528
	ds_read_b128 v[200:203], v224 offset:23552
	global_load_lds_dwordx4 v[204:205], off
	s_add_i32 m0, s94, 0x2000
	s_add_u32 s94, s28, 0x80000
	v_lshl_add_u64 v[226:227], s[28:29], 0, v[186:187]
	s_addc_u32 s95, s29, 0
	s_add_i32 s96, s96, s37
	global_load_lds_dwordx4 v[226:227], off
	v_lshl_add_u64 v[228:229], s[94:95], 0, v[16:17]
	s_mov_b32 m0, s96
	v_lshl_add_u64 v[230:231], s[52:53], 0, v[188:189]
	global_load_lds_dwordx4 v[228:229], off
	v_lshl_add_u64 v[228:229], s[94:95], 0, v[186:187]
	s_add_i32 m0, s96, 0x2000
	s_nop 0
	global_load_lds_dwordx4 v[228:229], off
	v_lshl_add_u64 v[228:229], s[52:53], 0, v[190:191]
	s_mov_b32 m0, s59
	s_nop 0
	global_load_lds_dwordx4 v[228:229], off
	s_mov_b32 m0, s83
	s_nop 0
	global_load_lds_dwordx4 v[230:231], off
	s_waitcnt vmcnt(8)
	s_waitcnt lgkmcnt(0)
	s_barrier
	s_nop 0
	s_waitcnt lgkmcnt(0)
	v_mfma_f32_16x16x32_bf16 v[62:65], v[130:133], v[162:165], v[62:65]
	v_mfma_f32_16x16x32_bf16 v[58:61], v[138:141], v[162:165], v[58:61]
	v_mfma_f32_16x16x32_bf16 v[50:53], v[130:133], v[170:173], v[50:53]
	v_mfma_f32_16x16x32_bf16 v[42:45], v[138:141], v[170:173], v[42:45]
	v_mfma_f32_16x16x32_bf16 v[34:37], v[130:133], v[178:181], v[34:37]
	v_mfma_f32_16x16x32_bf16 v[26:29], v[138:141], v[178:181], v[26:29]
	v_mfma_f32_16x16x32_bf16 v[18:21], v[130:133], v[196:199], v[18:21]
	v_mfma_f32_16x16x32_bf16 v[8:11], v[138:141], v[196:199], v[8:11]
	v_mfma_f32_16x16x32_bf16 v[62:65], v[134:137], v[166:169], v[62:65]
	v_mfma_f32_16x16x32_bf16 v[58:61], v[142:145], v[166:169], v[58:61]
	v_mfma_f32_16x16x32_bf16 v[50:53], v[134:137], v[174:177], v[50:53]
	v_mfma_f32_16x16x32_bf16 v[42:45], v[142:145], v[174:177], v[42:45]
	v_mfma_f32_16x16x32_bf16 v[34:37], v[134:137], v[182:185], v[34:37]
	v_mfma_f32_16x16x32_bf16 v[26:29], v[142:145], v[182:185], v[26:29]
	v_mfma_f32_16x16x32_bf16 v[18:21], v[134:137], v[200:203], v[18:21]
	v_mfma_f32_16x16x32_bf16 v[8:11], v[142:145], v[200:203], v[8:11]
	s_nop 0
	s_nop 0
	v_mfma_f32_16x16x32_bf16 v[54:57], v[146:149], v[162:165], v[54:57]
	v_mfma_f32_16x16x32_bf16 v[46:49], v[154:157], v[162:165], v[46:49]
	v_mfma_f32_16x16x32_bf16 v[38:41], v[146:149], v[170:173], v[38:41]
	v_mfma_f32_16x16x32_bf16 v[30:33], v[154:157], v[170:173], v[30:33]
	v_mfma_f32_16x16x32_bf16 v[22:25], v[146:149], v[178:181], v[22:25]
	v_mfma_f32_16x16x32_bf16 v[12:15], v[154:157], v[178:181], v[12:15]
	v_mfma_f32_16x16x32_bf16 v[4:7], v[146:149], v[196:199], v[4:7]
	v_mfma_f32_16x16x32_bf16 v[0:3], v[154:157], v[196:199], v[0:3]
	v_mfma_f32_16x16x32_bf16 v[54:57], v[150:153], v[166:169], v[54:57]
	v_mfma_f32_16x16x32_bf16 v[46:49], v[158:161], v[166:169], v[46:49]
	v_mfma_f32_16x16x32_bf16 v[38:41], v[150:153], v[174:177], v[38:41]
	v_mfma_f32_16x16x32_bf16 v[30:33], v[158:161], v[174:177], v[30:33]
	v_mfma_f32_16x16x32_bf16 v[22:25], v[150:153], v[182:185], v[22:25]
	v_mfma_f32_16x16x32_bf16 v[12:15], v[158:161], v[182:185], v[12:15]
	v_mfma_f32_16x16x32_bf16 v[4:7], v[150:153], v[200:203], v[4:7]
	v_mfma_f32_16x16x32_bf16 v[0:3], v[158:161], v[200:203], v[0:3]
	s_nop 0
	s_barrier
	s_add_i32 s94, 0, 0x18000
	s_add_i32 s95, 0, 0x1c000
	v_add_u32_e32 v142, s94, v207
	v_add_u32_e32 v158, s95, v207
	ds_read_b128 v[130:133], v142
	ds_read_b128 v[134:137], v142 offset:1024
	ds_read_b128 v[138:141], v142 offset:2048
	ds_read_b128 v[142:145], v142 offset:3072
	ds_read_b128 v[146:149], v158
	ds_read_b128 v[150:153], v158 offset:1024
	ds_read_b128 v[154:157], v158 offset:2048
	ds_read_b128 v[158:161], v158 offset:3072
	s_add_u32 s52, s52, 0x80000
	s_addc_u32 s53, s53, 0
	s_mov_b32 m0, s84
	v_lshl_add_u64 v[232:233], s[52:53], 0, v[190:191]
	ds_read_b128 v[162:165], v224 offset:32768
	ds_read_b128 v[166:169], v224 offset:33792
	ds_read_b128 v[170:173], v224 offset:34816
	ds_read_b128 v[174:177], v224 offset:35840
	ds_read_b128 v[178:181], v224 offset:36864
	ds_read_b128 v[182:185], v224 offset:37888
	ds_read_b128 v[196:199], v224 offset:38912
	ds_read_b128 v[200:203], v224 offset:39936
	global_load_lds_dwordx4 v[232:233], off
	v_lshl_add_u64 v[232:233], s[52:53], 0, v[188:189]
	s_mov_b32 m0, s85
	s_nop 0
	global_load_lds_dwordx4 v[232:233], off
	s_waitcnt vmcnt(8)
	s_waitcnt lgkmcnt(0)
	s_barrier
	s_nop 0
	s_waitcnt lgkmcnt(0)
	v_mfma_f32_16x16x32_bf16 v[126:129], v[130:133], v[162:165], v[126:129]
	v_mfma_f32_16x16x32_bf16 v[122:125], v[138:141], v[162:165], v[122:125]
	v_mfma_f32_16x16x32_bf16 v[114:117], v[130:133], v[170:173], v[114:117]
	v_mfma_f32_16x16x32_bf16 v[106:109], v[138:141], v[170:173], v[106:109]
	v_mfma_f32_16x16x32_bf16 v[98:101], v[130:133], v[178:181], v[98:101]
	v_mfma_f32_16x16x32_bf16 v[90:93], v[138:141], v[178:181], v[90:93]
	v_mfma_f32_16x16x32_bf16 v[82:85], v[130:133], v[196:199], v[82:85]
	v_mfma_f32_16x16x32_bf16 v[74:77], v[138:141], v[196:199], v[74:77]
	v_mfma_f32_16x16x32_bf16 v[126:129], v[134:137], v[166:169], v[126:129]
	v_mfma_f32_16x16x32_bf16 v[122:125], v[142:145], v[166:169], v[122:125]
	v_mfma_f32_16x16x32_bf16 v[114:117], v[134:137], v[174:177], v[114:117]
	v_mfma_f32_16x16x32_bf16 v[106:109], v[142:145], v[174:177], v[106:109]
	v_mfma_f32_16x16x32_bf16 v[98:101], v[134:137], v[182:185], v[98:101]
	v_mfma_f32_16x16x32_bf16 v[90:93], v[142:145], v[182:185], v[90:93]
	v_mfma_f32_16x16x32_bf16 v[82:85], v[134:137], v[200:203], v[82:85]
	v_mfma_f32_16x16x32_bf16 v[74:77], v[142:145], v[200:203], v[74:77]
	s_nop 0
	s_nop 0
	v_mfma_f32_16x16x32_bf16 v[118:121], v[146:149], v[162:165], v[118:121]
	v_mfma_f32_16x16x32_bf16 v[110:113], v[154:157], v[162:165], v[110:113]
	v_mfma_f32_16x16x32_bf16 v[102:105], v[146:149], v[170:173], v[102:105]
	v_mfma_f32_16x16x32_bf16 v[94:97], v[154:157], v[170:173], v[94:97]
	v_mfma_f32_16x16x32_bf16 v[86:89], v[146:149], v[178:181], v[86:89]
	v_mfma_f32_16x16x32_bf16 v[78:81], v[154:157], v[178:181], v[78:81]
	v_mfma_f32_16x16x32_bf16 v[70:73], v[146:149], v[196:199], v[70:73]
	v_mfma_f32_16x16x32_bf16 v[66:69], v[154:157], v[196:199], v[66:69]
	v_mfma_f32_16x16x32_bf16 v[118:121], v[150:153], v[166:169], v[118:121]
	v_mfma_f32_16x16x32_bf16 v[110:113], v[158:161], v[166:169], v[110:113]
	v_mfma_f32_16x16x32_bf16 v[102:105], v[150:153], v[174:177], v[102:105]
	v_mfma_f32_16x16x32_bf16 v[94:97], v[158:161], v[174:177], v[94:97]
	v_mfma_f32_16x16x32_bf16 v[86:89], v[150:153], v[182:185], v[86:89]
	v_mfma_f32_16x16x32_bf16 v[78:81], v[158:161], v[182:185], v[78:81]
	v_mfma_f32_16x16x32_bf16 v[70:73], v[150:153], v[200:203], v[70:73]
	v_mfma_f32_16x16x32_bf16 v[66:69], v[158:161], v[200:203], v[66:69]
	s_nop 0
	s_barrier
	s_add_i32 s52, s94, s37
	v_lshl_add_u64 v[204:205], v[204:205], 0, s[34:35]
	s_mov_b32 m0, s52
	ds_read_b128 v[162:165], v224 offset:49152
	ds_read_b128 v[166:169], v224 offset:50176
	ds_read_b128 v[170:173], v224 offset:51200
	ds_read_b128 v[174:177], v224 offset:52224
	ds_read_b128 v[178:181], v224 offset:53248
	ds_read_b128 v[182:185], v224 offset:54272
	ds_read_b128 v[196:199], v224 offset:55296
	ds_read_b128 v[200:203], v224 offset:56320
	global_load_lds_dwordx4 v[204:205], off
	s_add_i32 m0, s52, 0x2000
	s_add_u32 s28, s28, 0x80080
	v_lshl_add_u64 v[204:205], v[226:227], 0, s[34:35]
	s_addc_u32 s29, s29, 0
	s_add_i32 s52, s95, s37
	global_load_lds_dwordx4 v[204:205], off
	v_lshl_add_u64 v[204:205], s[28:29], 0, v[16:17]
	s_mov_b32 m0, s52
	s_nop 0
	global_load_lds_dwordx4 v[204:205], off
	v_lshl_add_u64 v[204:205], s[28:29], 0, v[186:187]
	s_add_i32 m0, s52, 0x2000
	s_nop 0
	global_load_lds_dwordx4 v[204:205], off
	v_lshl_add_u64 v[204:205], v[228:229], 0, s[34:35]
	s_mov_b32 m0, s88
	s_nop 0
	global_load_lds_dwordx4 v[204:205], off
	v_lshl_add_u64 v[204:205], v[230:231], 0, s[34:35]
	s_mov_b32 m0, s89
	s_nop 0
	global_load_lds_dwordx4 v[204:205], off
	s_waitcnt vmcnt(8)
	s_waitcnt lgkmcnt(0)
	s_barrier
	s_nop 0
	s_waitcnt lgkmcnt(0)
	v_mfma_f32_16x16x32_bf16 v[62:65], v[130:133], v[162:165], v[62:65]
	v_mfma_f32_16x16x32_bf16 v[58:61], v[138:141], v[162:165], v[58:61]
	v_mfma_f32_16x16x32_bf16 v[50:53], v[130:133], v[170:173], v[50:53]
	v_mfma_f32_16x16x32_bf16 v[42:45], v[138:141], v[170:173], v[42:45]
	v_mfma_f32_16x16x32_bf16 v[34:37], v[130:133], v[178:181], v[34:37]
	v_mfma_f32_16x16x32_bf16 v[26:29], v[138:141], v[178:181], v[26:29]
	v_mfma_f32_16x16x32_bf16 v[18:21], v[130:133], v[196:199], v[18:21]
	v_mfma_f32_16x16x32_bf16 v[8:11], v[138:141], v[196:199], v[8:11]
	v_mfma_f32_16x16x32_bf16 v[62:65], v[134:137], v[166:169], v[62:65]
	v_mfma_f32_16x16x32_bf16 v[58:61], v[142:145], v[166:169], v[58:61]
	v_mfma_f32_16x16x32_bf16 v[50:53], v[134:137], v[174:177], v[50:53]
	v_mfma_f32_16x16x32_bf16 v[42:45], v[142:145], v[174:177], v[42:45]
	v_mfma_f32_16x16x32_bf16 v[34:37], v[134:137], v[182:185], v[34:37]
	v_mfma_f32_16x16x32_bf16 v[26:29], v[142:145], v[182:185], v[26:29]
	v_mfma_f32_16x16x32_bf16 v[18:21], v[134:137], v[200:203], v[18:21]
	v_mfma_f32_16x16x32_bf16 v[8:11], v[142:145], v[200:203], v[8:11]
	s_nop 0
	s_nop 0
	v_mfma_f32_16x16x32_bf16 v[54:57], v[146:149], v[162:165], v[54:57]
	v_mfma_f32_16x16x32_bf16 v[46:49], v[154:157], v[162:165], v[46:49]
	v_mfma_f32_16x16x32_bf16 v[38:41], v[146:149], v[170:173], v[38:41]
	v_mfma_f32_16x16x32_bf16 v[30:33], v[154:157], v[170:173], v[30:33]
	v_mfma_f32_16x16x32_bf16 v[22:25], v[146:149], v[178:181], v[22:25]
	v_mfma_f32_16x16x32_bf16 v[12:15], v[154:157], v[178:181], v[12:15]
	v_mfma_f32_16x16x32_bf16 v[4:7], v[146:149], v[196:199], v[4:7]
	v_mfma_f32_16x16x32_bf16 v[0:3], v[154:157], v[196:199], v[0:3]
	v_mfma_f32_16x16x32_bf16 v[54:57], v[150:153], v[166:169], v[54:57]
	v_mfma_f32_16x16x32_bf16 v[46:49], v[158:161], v[166:169], v[46:49]
	v_mfma_f32_16x16x32_bf16 v[38:41], v[150:153], v[174:177], v[38:41]
	v_mfma_f32_16x16x32_bf16 v[30:33], v[158:161], v[174:177], v[30:33]
	v_mfma_f32_16x16x32_bf16 v[22:25], v[150:153], v[182:185], v[22:25]
	v_mfma_f32_16x16x32_bf16 v[12:15], v[158:161], v[182:185], v[12:15]
	v_mfma_f32_16x16x32_bf16 v[4:7], v[150:153], v[200:203], v[4:7]
	v_mfma_f32_16x16x32_bf16 v[0:3], v[158:161], v[200:203], v[0:3]
	s_nop 0
	s_barrier
	s_add_i32 s93, s93, 2
	s_add_u32 s50, s50, 0x100
	s_addc_u32 s51, s51, 0
	s_add_u32 vcc_hi, vcc_hi, 0x100
	s_addc_u32 s92, s92, 0
	s_cmp_gt_u32 s93, 29
	s_cbranch_scc0 .LBB0_787
	s_and_b64 vcc, exec, s[22:23]
	s_cbranch_vccz .LBB0_790
	s_barrier

.LBB0_803:
	s_setprio 0
	s_waitcnt vmcnt(0)
	v_readlane_b32 s10, v255, 35
	v_readlane_b32 s11, v255, 36
	s_mov_b64 s[90:91], s[62:63]
	s_barrier
	v_readlane_b32 s86, v255, 41
	s_cmp_lg_u32 s86, 0
	s_cbranch_scc1 .Ldc_u0_skip
	s_movk_i32 s87, 64
	s_cmp_gt_u32 s60, s87
	s_cselect_b32 s87, s87, 0
	s_cmp_lt_u32 s2, s87
	s_cbranch_scc1 .Ldc_u0_skip
	v_writelane_b32 v255, s24, 48
	v_writelane_b32 v255, s26, 49
	v_writelane_b32 v255, s27, 50
	v_writelane_b32 v255, s28, 51
	v_writelane_b32 v255, s29, 52
	v_writelane_b32 v255, s37, 53
	v_writelane_b32 v255, s40, 54
	v_writelane_b32 v255, s41, 55
	v_writelane_b32 v255, s42, 56
	v_writelane_b32 v255, s43, 57
	v_writelane_b32 v255, s48, 58
	v_writelane_b32 v255, s49, 59
	v_writelane_b32 v255, s56, 60
	v_writelane_b32 v255, s57, 61
	v_writelane_b32 v255, s83, 62
	v_writelane_b32 v255, s87, 47
	s_sub_u32 s2, s2, s87
	s_sub_u32 s60, s60, s87
	v_readlane_b32 s18, v255, 8
	v_readlane_b32 s19, v255, 9
	s_load_dwordx2 s[46:47], s[18:19], 0xd0
	s_load_dwordx2 s[56:57], s[18:19], 0xd8
	s_nop 0
	s_load_dwordx2 s[18:19], s[18:19], 0xf0
	s_waitcnt lgkmcnt(0)

.LBB0_917:
	s_and_b64 vcc, exec, s[14:15]
	s_cbranch_vccz .Lsp_I
	s_setprio 1

.LBB0_920:
	s_add_u32 s28, s46, 0xfff80080
	s_addc_u32 s29, s47, -1
	s_add_i32 s91, 0, 0x10000
	s_cmp_eq_u32 s90, 28
	s_cselect_b32 s49, s27, s29
	s_cselect_b32 s48, s86, s28
	s_cselect_b32 s29, s23, s89
	s_cselect_b32 s28, s87, s88
	s_add_i32 s94, 0, 0x14000
	v_add_u32_e32 v156, s91, v141
	v_add_u32_e32 v172, s94, v141
	ds_read_b128 v[144:147], v156
	ds_read_b128 v[148:151], v156 offset:1024
	ds_read_b128 v[152:155], v156 offset:2048
	ds_read_b128 v[156:159], v156 offset:3072
	ds_read_b128 v[160:163], v172
	ds_read_b128 v[164:167], v172 offset:1024
	ds_read_b128 v[168:171], v172 offset:2048
	ds_read_b128 v[172:175], v172 offset:3072
	v_lshl_add_u64 v[216:217], s[46:47], 0, v[136:137]
	s_add_i32 m0, s45, 0xc000
	ds_read_b128 v[176:179], v143
	ds_read_b128 v[180:183], v143 offset:1024
	ds_read_b128 v[184:187], v143 offset:2048
	ds_read_b128 v[188:191], v143 offset:3072
	ds_read_b128 v[192:195], v143 offset:4096
	ds_read_b128 v[196:199], v143 offset:5120
	ds_read_b128 v[200:203], v143 offset:6144
	ds_read_b128 v[204:207], v143 offset:7168
	global_load_lds_dwordx4 v[216:217], off
	v_lshl_add_u64 v[216:217], s[46:47], 0, v[138:139]
	s_add_i32 m0, s45, 0xe000
	s_nop 0
	global_load_lds_dwordx4 v[216:217], off
	s_waitcnt vmcnt(8)
	s_waitcnt lgkmcnt(0)
	s_barrier
	s_nop 0
	s_waitcnt lgkmcnt(0)
	v_mfma_f32_16x16x32_bf16 v[126:129], v[144:147], v[176:179], v[126:129]
	v_mfma_f32_16x16x32_bf16 v[118:121], v[152:155], v[176:179], v[118:121]
	v_mfma_f32_16x16x32_bf16 v[110:113], v[144:147], v[184:187], v[110:113]
	v_mfma_f32_16x16x32_bf16 v[102:105], v[152:155], v[184:187], v[102:105]
	v_mfma_f32_16x16x32_bf16 v[94:97], v[144:147], v[192:195], v[94:97]
	v_mfma_f32_16x16x32_bf16 v[86:89], v[152:155], v[192:195], v[86:89]
	v_mfma_f32_16x16x32_bf16 v[78:81], v[144:147], v[200:203], v[78:81]
	v_mfma_f32_16x16x32_bf16 v[70:73], v[152:155], v[200:203], v[70:73]
	v_mfma_f32_16x16x32_bf16 v[126:129], v[148:151], v[180:183], v[126:129]
	v_mfma_f32_16x16x32_bf16 v[118:121], v[156:159], v[180:183], v[118:121]
	v_mfma_f32_16x16x32_bf16 v[110:113], v[148:151], v[188:191], v[110:113]
	v_mfma_f32_16x16x32_bf16 v[102:105], v[156:159], v[188:191], v[102:105]
	v_mfma_f32_16x16x32_bf16 v[94:97], v[148:151], v[196:199], v[94:97]
	v_mfma_f32_16x16x32_bf16 v[86:89], v[156:159], v[196:199], v[86:89]
	v_mfma_f32_16x16x32_bf16 v[78:81], v[148:151], v[204:207], v[78:81]
	v_mfma_f32_16x16x32_bf16 v[70:73], v[156:159], v[204:207], v[70:73]
	s_nop 0
	s_nop 0
	v_mfma_f32_16x16x32_bf16 v[122:125], v[160:163], v[176:179], v[122:125]
	v_mfma_f32_16x16x32_bf16 v[114:117], v[168:171], v[176:179], v[114:117]
	v_mfma_f32_16x16x32_bf16 v[106:109], v[160:163], v[184:187], v[106:109]
	v_mfma_f32_16x16x32_bf16 v[98:101], v[168:171], v[184:187], v[98:101]
	v_mfma_f32_16x16x32_bf16 v[90:93], v[160:163], v[192:195], v[90:93]
	v_mfma_f32_16x16x32_bf16 v[82:85], v[168:171], v[192:195], v[82:85]
	v_mfma_f32_16x16x32_bf16 v[74:77], v[160:163], v[200:203], v[74:77]
	v_mfma_f32_16x16x32_bf16 v[66:69], v[168:171], v[200:203], v[66:69]
	v_mfma_f32_16x16x32_bf16 v[122:125], v[164:167], v[180:183], v[122:125]
	v_mfma_f32_16x16x32_bf16 v[114:117], v[172:175], v[180:183], v[114:117]
	v_mfma_f32_16x16x32_bf16 v[106:109], v[164:167], v[188:191], v[106:109]
	v_mfma_f32_16x16x32_bf16 v[98:101], v[172:175], v[188:191], v[98:101]
	v_mfma_f32_16x16x32_bf16 v[90:93], v[164:167], v[196:199], v[90:93]
	v_mfma_f32_16x16x32_bf16 v[82:85], v[172:175], v[196:199], v[82:85]
	v_mfma_f32_16x16x32_bf16 v[74:77], v[164:167], v[204:207], v[74:77]
	v_mfma_f32_16x16x32_bf16 v[66:69], v[172:175], v[204:207], v[66:69]
	s_nop 0
	s_barrier
	s_add_i32 s91, s91, s37
	v_lshl_add_u64 v[216:217], s[28:29], 0, v[16:17]
	s_mov_b32 m0, s91
	ds_read_b128 v[176:179], v143 offset:16384
	ds_read_b128 v[180:183], v143 offset:17408
	ds_read_b128 v[184:187], v143 offset:18432
	ds_read_b128 v[188:191], v143 offset:19456
	ds_read_b128 v[192:195], v143 offset:20480
	ds_read_b128 v[196:199], v143 offset:21504
	ds_read_b128 v[200:203], v143 offset:22528
	ds_read_b128 v[204:207], v143 offset:23552
	global_load_lds_dwordx4 v[216:217], off
	s_add_i32 m0, s91, 0x2000
	s_add_u32 s92, s28, 0x80000
	v_lshl_add_u64 v[224:225], s[28:29], 0, v[130:131]
	s_addc_u32 s93, s29, 0
	s_add_i32 s91, s94, s37
	global_load_lds_dwordx4 v[224:225], off
	v_lshl_add_u64 v[226:227], s[92:93], 0, v[16:17]
	s_mov_b32 m0, s91
	v_lshl_add_u64 v[228:229], s[48:49], 0, v[132:133]
	global_load_lds_dwordx4 v[226:227], off
	v_lshl_add_u64 v[226:227], s[92:93], 0, v[130:131]
	s_add_i32 m0, s91, 0x2000
	s_nop 0
	global_load_lds_dwordx4 v[226:227], off
	v_lshl_add_u64 v[226:227], s[48:49], 0, v[134:135]
	s_mov_b32 m0, s45
	s_nop 0
	global_load_lds_dwordx4 v[226:227], off
	s_mov_b32 m0, s53
	s_nop 0
	global_load_lds_dwordx4 v[228:229], off
	s_waitcnt vmcnt(8)
	s_waitcnt lgkmcnt(0)
	s_barrier
	s_nop 0
	s_waitcnt lgkmcnt(0)
	v_mfma_f32_16x16x32_bf16 v[62:65], v[144:147], v[176:179], v[62:65]
	v_mfma_f32_16x16x32_bf16 v[54:57], v[152:155], v[176:179], v[54:57]
	v_mfma_f32_16x16x32_bf16 v[46:49], v[144:147], v[184:187], v[46:49]
	v_mfma_f32_16x16x32_bf16 v[38:41], v[152:155], v[184:187], v[38:41]
	v_mfma_f32_16x16x32_bf16 v[30:33], v[144:147], v[192:195], v[30:33]
	v_mfma_f32_16x16x32_bf16 v[22:25], v[152:155], v[192:195], v[22:25]
	v_mfma_f32_16x16x32_bf16 v[12:15], v[144:147], v[200:203], v[12:15]
	v_mfma_f32_16x16x32_bf16 v[4:7], v[152:155], v[200:203], v[4:7]
	v_mfma_f32_16x16x32_bf16 v[62:65], v[148:151], v[180:183], v[62:65]
	v_mfma_f32_16x16x32_bf16 v[54:57], v[156:159], v[180:183], v[54:57]
	v_mfma_f32_16x16x32_bf16 v[46:49], v[148:151], v[188:191], v[46:49]
	v_mfma_f32_16x16x32_bf16 v[38:41], v[156:159], v[188:191], v[38:41]
	v_mfma_f32_16x16x32_bf16 v[30:33], v[148:151], v[196:199], v[30:33]
	v_mfma_f32_16x16x32_bf16 v[22:25], v[156:159], v[196:199], v[22:25]
	v_mfma_f32_16x16x32_bf16 v[12:15], v[148:151], v[204:207], v[12:15]
	v_mfma_f32_16x16x32_bf16 v[4:7], v[156:159], v[204:207], v[4:7]
	s_nop 0
	s_nop 0
	v_mfma_f32_16x16x32_bf16 v[58:61], v[160:163], v[176:179], v[58:61]
	v_mfma_f32_16x16x32_bf16 v[50:53], v[168:171], v[176:179], v[50:53]
	v_mfma_f32_16x16x32_bf16 v[42:45], v[160:163], v[184:187], v[42:45]
	v_mfma_f32_16x16x32_bf16 v[34:37], v[168:171], v[184:187], v[34:37]
	v_mfma_f32_16x16x32_bf16 v[26:29], v[160:163], v[192:195], v[26:29]
	v_mfma_f32_16x16x32_bf16 v[18:21], v[168:171], v[192:195], v[18:21]
	v_mfma_f32_16x16x32_bf16 v[8:11], v[160:163], v[200:203], v[8:11]
	v_mfma_f32_16x16x32_bf16 v[0:3], v[168:171], v[200:203], v[0:3]
	v_mfma_f32_16x16x32_bf16 v[58:61], v[164:167], v[180:183], v[58:61]
	v_mfma_f32_16x16x32_bf16 v[50:53], v[172:175], v[180:183], v[50:53]
	v_mfma_f32_16x16x32_bf16 v[42:45], v[164:167], v[188:191], v[42:45]
	v_mfma_f32_16x16x32_bf16 v[34:37], v[172:175], v[188:191], v[34:37]
	v_mfma_f32_16x16x32_bf16 v[26:29], v[164:167], v[196:199], v[26:29]
	v_mfma_f32_16x16x32_bf16 v[18:21], v[172:175], v[196:199], v[18:21]
	v_mfma_f32_16x16x32_bf16 v[8:11], v[164:167], v[204:207], v[8:11]
	v_mfma_f32_16x16x32_bf16 v[0:3], v[172:175], v[204:207], v[0:3]
	s_nop 0
	s_barrier
	s_add_i32 s91, 0, 0x18000
	s_add_i32 s92, 0, 0x1c000
	v_add_u32_e32 v156, s91, v141
	v_add_u32_e32 v172, s92, v141
	ds_read_b128 v[144:147], v156
	ds_read_b128 v[148:151], v156 offset:1024
	ds_read_b128 v[152:155], v156 offset:2048
	ds_read_b128 v[156:159], v156 offset:3072
	ds_read_b128 v[160:163], v172
	ds_read_b128 v[164:167], v172 offset:1024
	ds_read_b128 v[168:171], v172 offset:2048
	ds_read_b128 v[172:175], v172 offset:3072
	s_add_u32 s48, s48, 0x80000
	s_addc_u32 s49, s49, 0
	s_mov_b32 m0, s57
	v_lshl_add_u64 v[230:231], s[48:49], 0, v[134:135]
	ds_read_b128 v[176:179], v143 offset:32768
	ds_read_b128 v[180:183], v143 offset:33792
	ds_read_b128 v[184:187], v143 offset:34816
	ds_read_b128 v[188:191], v143 offset:35840
	ds_read_b128 v[192:195], v143 offset:36864
	ds_read_b128 v[196:199], v143 offset:37888
	ds_read_b128 v[200:203], v143 offset:38912
	ds_read_b128 v[204:207], v143 offset:39936
	global_load_lds_dwordx4 v[230:231], off
	v_lshl_add_u64 v[230:231], s[48:49], 0, v[132:133]
	s_mov_b32 m0, s58
	s_nop 0
	global_load_lds_dwordx4 v[230:231], off
	s_waitcnt vmcnt(8)
	s_waitcnt lgkmcnt(0)
	s_barrier
	s_nop 0
	s_waitcnt lgkmcnt(0)
	v_mfma_f32_16x16x32_bf16 v[126:129], v[144:147], v[176:179], v[126:129]
	v_mfma_f32_16x16x32_bf16 v[118:121], v[152:155], v[176:179], v[118:121]
	v_mfma_f32_16x16x32_bf16 v[110:113], v[144:147], v[184:187], v[110:113]
	v_mfma_f32_16x16x32_bf16 v[102:105], v[152:155], v[184:187], v[102:105]
	v_mfma_f32_16x16x32_bf16 v[94:97], v[144:147], v[192:195], v[94:97]
	v_mfma_f32_16x16x32_bf16 v[86:89], v[152:155], v[192:195], v[86:89]
	v_mfma_f32_16x16x32_bf16 v[78:81], v[144:147], v[200:203], v[78:81]
	v_mfma_f32_16x16x32_bf16 v[70:73], v[152:155], v[200:203], v[70:73]
	v_mfma_f32_16x16x32_bf16 v[126:129], v[148:151], v[180:183], v[126:129]
	v_mfma_f32_16x16x32_bf16 v[118:121], v[156:159], v[180:183], v[118:121]
	v_mfma_f32_16x16x32_bf16 v[110:113], v[148:151], v[188:191], v[110:113]
	v_mfma_f32_16x16x32_bf16 v[102:105], v[156:159], v[188:191], v[102:105]
	v_mfma_f32_16x16x32_bf16 v[94:97], v[148:151], v[196:199], v[94:97]
	v_mfma_f32_16x16x32_bf16 v[86:89], v[156:159], v[196:199], v[86:89]
	v_mfma_f32_16x16x32_bf16 v[78:81], v[148:151], v[204:207], v[78:81]
	v_mfma_f32_16x16x32_bf16 v[70:73], v[156:159], v[204:207], v[70:73]
	s_nop 0
	s_nop 0
	v_mfma_f32_16x16x32_bf16 v[122:125], v[160:163], v[176:179], v[122:125]
	v_mfma_f32_16x16x32_bf16 v[114:117], v[168:171], v[176:179], v[114:117]
	v_mfma_f32_16x16x32_bf16 v[106:109], v[160:163], v[184:187], v[106:109]
	v_mfma_f32_16x16x32_bf16 v[98:101], v[168:171], v[184:187], v[98:101]
	v_mfma_f32_16x16x32_bf16 v[90:93], v[160:163], v[192:195], v[90:93]
	v_mfma_f32_16x16x32_bf16 v[82:85], v[168:171], v[192:195], v[82:85]
	v_mfma_f32_16x16x32_bf16 v[74:77], v[160:163], v[200:203], v[74:77]
	v_mfma_f32_16x16x32_bf16 v[66:69], v[168:171], v[200:203], v[66:69]
	v_mfma_f32_16x16x32_bf16 v[122:125], v[164:167], v[180:183], v[122:125]
	v_mfma_f32_16x16x32_bf16 v[114:117], v[172:175], v[180:183], v[114:117]
	v_mfma_f32_16x16x32_bf16 v[106:109], v[164:167], v[188:191], v[106:109]
	v_mfma_f32_16x16x32_bf16 v[98:101], v[172:175], v[188:191], v[98:101]
	v_mfma_f32_16x16x32_bf16 v[90:93], v[164:167], v[196:199], v[90:93]
	v_mfma_f32_16x16x32_bf16 v[82:85], v[172:175], v[196:199], v[82:85]
	v_mfma_f32_16x16x32_bf16 v[74:77], v[164:167], v[204:207], v[74:77]
	v_mfma_f32_16x16x32_bf16 v[66:69], v[172:175], v[204:207], v[66:69]
	s_nop 0
	s_barrier
	s_add_i32 s48, s91, s37
	v_lshl_add_u64 v[216:217], v[216:217], 0, s[34:35]
	s_mov_b32 m0, s48
	ds_read_b128 v[176:179], v143 offset:49152
	ds_read_b128 v[180:183], v143 offset:50176
	ds_read_b128 v[184:187], v143 offset:51200
	ds_read_b128 v[188:191], v143 offset:52224
	ds_read_b128 v[192:195], v143 offset:53248
	ds_read_b128 v[196:199], v143 offset:54272
	ds_read_b128 v[200:203], v143 offset:55296
	ds_read_b128 v[204:207], v143 offset:56320
	global_load_lds_dwordx4 v[216:217], off
	s_add_i32 m0, s48, 0x2000
	s_add_u32 s28, s28, 0x80080
	v_lshl_add_u64 v[216:217], v[224:225], 0, s[34:35]
	s_addc_u32 s29, s29, 0
	s_add_i32 s48, s92, s37
	global_load_lds_dwordx4 v[216:217], off
	v_lshl_add_u64 v[216:217], s[28:29], 0, v[16:17]
	s_mov_b32 m0, s48
	s_nop 0
	global_load_lds_dwordx4 v[216:217], off
	v_lshl_add_u64 v[216:217], s[28:29], 0, v[130:131]
	s_add_i32 m0, s48, 0x2000
	s_nop 0
	global_load_lds_dwordx4 v[216:217], off
	v_lshl_add_u64 v[216:217], v[226:227], 0, s[34:35]
	s_mov_b32 m0, s59
	s_nop 0
	global_load_lds_dwordx4 v[216:217], off
	v_lshl_add_u64 v[216:217], v[228:229], 0, s[34:35]
	s_mov_b32 m0, s83
	s_nop 0
	global_load_lds_dwordx4 v[216:217], off
	s_waitcnt vmcnt(8)
	s_waitcnt lgkmcnt(0)
	s_barrier
	s_nop 0
	s_waitcnt lgkmcnt(0)
	v_mfma_f32_16x16x32_bf16 v[62:65], v[144:147], v[176:179], v[62:65]
	v_mfma_f32_16x16x32_bf16 v[54:57], v[152:155], v[176:179], v[54:57]
	v_mfma_f32_16x16x32_bf16 v[46:49], v[144:147], v[184:187], v[46:49]
	v_mfma_f32_16x16x32_bf16 v[38:41], v[152:155], v[184:187], v[38:41]
	v_mfma_f32_16x16x32_bf16 v[30:33], v[144:147], v[192:195], v[30:33]
	v_mfma_f32_16x16x32_bf16 v[22:25], v[152:155], v[192:195], v[22:25]
	v_mfma_f32_16x16x32_bf16 v[12:15], v[144:147], v[200:203], v[12:15]
	v_mfma_f32_16x16x32_bf16 v[4:7], v[152:155], v[200:203], v[4:7]
	v_mfma_f32_16x16x32_bf16 v[62:65], v[148:151], v[180:183], v[62:65]
	v_mfma_f32_16x16x32_bf16 v[54:57], v[156:159], v[180:183], v[54:57]
	v_mfma_f32_16x16x32_bf16 v[46:49], v[148:151], v[188:191], v[46:49]
	v_mfma_f32_16x16x32_bf16 v[38:41], v[156:159], v[188:191], v[38:41]
	v_mfma_f32_16x16x32_bf16 v[30:33], v[148:151], v[196:199], v[30:33]
	v_mfma_f32_16x16x32_bf16 v[22:25], v[156:159], v[196:199], v[22:25]
	v_mfma_f32_16x16x32_bf16 v[12:15], v[148:151], v[204:207], v[12:15]
	v_mfma_f32_16x16x32_bf16 v[4:7], v[156:159], v[204:207], v[4:7]
	s_nop 0
	s_nop 0
	v_mfma_f32_16x16x32_bf16 v[58:61], v[160:163], v[176:179], v[58:61]
	v_mfma_f32_16x16x32_bf16 v[50:53], v[168:171], v[176:179], v[50:53]
	v_mfma_f32_16x16x32_bf16 v[42:45], v[160:163], v[184:187], v[42:45]
	v_mfma_f32_16x16x32_bf16 v[34:37], v[168:171], v[184:187], v[34:37]
	v_mfma_f32_16x16x32_bf16 v[26:29], v[160:163], v[192:195], v[26:29]
	v_mfma_f32_16x16x32_bf16 v[18:21], v[168:171], v[192:195], v[18:21]
	v_mfma_f32_16x16x32_bf16 v[8:11], v[160:163], v[200:203], v[8:11]
	v_mfma_f32_16x16x32_bf16 v[0:3], v[168:171], v[200:203], v[0:3]
	v_mfma_f32_16x16x32_bf16 v[58:61], v[164:167], v[180:183], v[58:61]
	v_mfma_f32_16x16x32_bf16 v[50:53], v[172:175], v[180:183], v[50:53]
	v_mfma_f32_16x16x32_bf16 v[42:45], v[164:167], v[188:191], v[42:45]
	v_mfma_f32_16x16x32_bf16 v[34:37], v[172:175], v[188:191], v[34:37]
	v_mfma_f32_16x16x32_bf16 v[26:29], v[164:167], v[196:199], v[26:29]
	v_mfma_f32_16x16x32_bf16 v[18:21], v[172:175], v[196:199], v[18:21]
	v_mfma_f32_16x16x32_bf16 v[8:11], v[164:167], v[204:207], v[8:11]
	v_mfma_f32_16x16x32_bf16 v[0:3], v[172:175], v[204:207], v[0:3]
	s_nop 0
	s_barrier
	s_add_i32 s90, s90, 2
	s_add_u32 s46, s46, 0x100
	s_addc_u32 s47, s47, 0
	s_add_u32 s88, s88, 0x100
	s_addc_u32 s89, s89, 0
	s_cmp_gt_u32 s90, 29
	s_cbranch_scc0 .LBB0_920
	s_and_b64 vcc, exec, s[18:19]
	s_cbranch_vccz .LBB0_923
	s_barrier

.LBB0_926:
	s_setprio 0
	s_waitcnt vmcnt(0)
	s_barrier
	v_readlane_b32 s86, v255, 41
	s_cmp_lg_u32 s86, 0
	s_cbranch_scc1 .Ldc_w0_skip
	s_movk_i32 s87, 96
	s_cmp_gt_u32 s60, s87
	s_cselect_b32 s87, s87, 0
	s_cmp_lt_u32 s2, s87
	s_cbranch_scc1 .Ldc_w0_skip
	v_writelane_b32 v255, s24, 48
	v_writelane_b32 v255, s26, 49
	v_writelane_b32 v255, s27, 50
	v_writelane_b32 v255, s28, 51
	v_writelane_b32 v255, s29, 52
	v_writelane_b32 v255, s37, 53
	v_writelane_b32 v255, s40, 54
	v_writelane_b32 v255, s41, 55
	v_writelane_b32 v255, s42, 56
	v_writelane_b32 v255, s43, 57
	v_writelane_b32 v255, s56, 58
	v_writelane_b32 v255, s83, 59
	v_writelane_b32 v255, s87, 47
	s_sub_u32 s2, s2, s87
	s_sub_u32 s60, s60, s87
	v_readlane_b32 s18, v255, 8
	v_readlane_b32 s19, v255, 9
	s_load_dwordx2 s[58:59], s[18:19], 0xe0
	s_nop 0
	s_load_dwordx2 s[18:19], s[18:19], 0xf0
	s_waitcnt lgkmcnt(0)

.LBB0_992:
	s_add_u32 s36, s26, 0x100
	s_addc_u32 s37, s27, 0
	s_add_i32 s87, 0, 0x10000
	s_cmpk_eq_i32 s86, 0x54
	s_cselect_b32 s41, s19, s37
	s_cselect_b32 s40, s18, s36
	s_cselect_b32 s29, s23, s43
	s_cselect_b32 s28, s22, s42
	s_add_i32 s88, 0, 0x14000
	v_add_u32_e32 v142, s87, v203
	v_add_u32_e32 v158, s88, v203
	ds_read_b128 v[130:133], v142
	ds_read_b128 v[134:137], v142 offset:1024
	ds_read_b128 v[138:141], v142 offset:2048
	ds_read_b128 v[142:145], v142 offset:3072
	ds_read_b128 v[146:149], v158
	ds_read_b128 v[150:153], v158 offset:1024
	ds_read_b128 v[154:157], v158 offset:2048
	ds_read_b128 v[158:161], v158 offset:3072
	v_lshl_add_u64 v[200:201], s[26:27], 0, v[188:189]
	s_add_i32 m0, s47, 0xc000
	ds_read_b128 v[162:165], v205
	ds_read_b128 v[166:169], v205 offset:1024
	ds_read_b128 v[170:173], v205 offset:2048
	ds_read_b128 v[174:177], v205 offset:3072
	ds_read_b128 v[178:181], v205 offset:4096
	ds_read_b128 v[192:195], v205 offset:5120
	ds_read_b128 v[196:199], v205 offset:6144
	ds_read_b128 v[224:227], v205 offset:7168
	global_load_lds_dwordx4 v[200:201], off
	v_lshl_add_u64 v[200:201], s[26:27], 0, v[190:191]
	s_add_i32 m0, s47, 0xe000
	s_nop 0
	global_load_lds_dwordx4 v[200:201], off
	s_waitcnt vmcnt(8)
	s_waitcnt lgkmcnt(0)
	s_barrier
	s_nop 0
	s_waitcnt lgkmcnt(0)
	v_mfma_f32_16x16x32_bf16 v[126:129], v[130:133], v[162:165], v[126:129]
	v_mfma_f32_16x16x32_bf16 v[122:125], v[138:141], v[162:165], v[122:125]
	v_mfma_f32_16x16x32_bf16 v[114:117], v[130:133], v[170:173], v[114:117]
	v_mfma_f32_16x16x32_bf16 v[106:109], v[138:141], v[170:173], v[106:109]
	v_mfma_f32_16x16x32_bf16 v[98:101], v[130:133], v[178:181], v[98:101]
	v_mfma_f32_16x16x32_bf16 v[90:93], v[138:141], v[178:181], v[90:93]
	v_mfma_f32_16x16x32_bf16 v[82:85], v[130:133], v[196:199], v[82:85]
	v_mfma_f32_16x16x32_bf16 v[74:77], v[138:141], v[196:199], v[74:77]
	v_mfma_f32_16x16x32_bf16 v[126:129], v[134:137], v[166:169], v[126:129]
	v_mfma_f32_16x16x32_bf16 v[122:125], v[142:145], v[166:169], v[122:125]
	v_mfma_f32_16x16x32_bf16 v[114:117], v[134:137], v[174:177], v[114:117]
	v_mfma_f32_16x16x32_bf16 v[106:109], v[142:145], v[174:177], v[106:109]
	v_mfma_f32_16x16x32_bf16 v[98:101], v[134:137], v[192:195], v[98:101]
	v_mfma_f32_16x16x32_bf16 v[90:93], v[142:145], v[192:195], v[90:93]
	v_mfma_f32_16x16x32_bf16 v[82:85], v[134:137], v[224:227], v[82:85]
	v_mfma_f32_16x16x32_bf16 v[74:77], v[142:145], v[224:227], v[74:77]
	s_nop 0
	s_nop 0
	v_mfma_f32_16x16x32_bf16 v[118:121], v[146:149], v[162:165], v[118:121]
	v_mfma_f32_16x16x32_bf16 v[110:113], v[154:157], v[162:165], v[110:113]
	v_mfma_f32_16x16x32_bf16 v[102:105], v[146:149], v[170:173], v[102:105]
	v_mfma_f32_16x16x32_bf16 v[94:97], v[154:157], v[170:173], v[94:97]
	v_mfma_f32_16x16x32_bf16 v[86:89], v[146:149], v[178:181], v[86:89]
	v_mfma_f32_16x16x32_bf16 v[78:81], v[154:157], v[178:181], v[78:81]
	v_mfma_f32_16x16x32_bf16 v[70:73], v[146:149], v[196:199], v[70:73]
	v_mfma_f32_16x16x32_bf16 v[66:69], v[154:157], v[196:199], v[66:69]
	v_mfma_f32_16x16x32_bf16 v[118:121], v[150:153], v[166:169], v[118:121]
	v_mfma_f32_16x16x32_bf16 v[110:113], v[158:161], v[166:169], v[110:113]
	v_mfma_f32_16x16x32_bf16 v[102:105], v[150:153], v[174:177], v[102:105]
	v_mfma_f32_16x16x32_bf16 v[94:97], v[158:161], v[174:177], v[94:97]
	v_mfma_f32_16x16x32_bf16 v[86:89], v[150:153], v[192:195], v[86:89]
	v_mfma_f32_16x16x32_bf16 v[78:81], v[158:161], v[192:195], v[78:81]
	v_mfma_f32_16x16x32_bf16 v[70:73], v[150:153], v[224:227], v[70:73]
	v_mfma_f32_16x16x32_bf16 v[66:69], v[158:161], v[224:227], v[66:69]
	s_nop 0
	s_barrier
	s_add_i32 s26, s87, s45
	v_lshl_add_u64 v[200:201], s[28:29], 0, v[16:17]
	s_mov_b32 m0, s26
	ds_read_b128 v[162:165], v205 offset:16384
	ds_read_b128 v[166:169], v205 offset:17408
	ds_read_b128 v[170:173], v205 offset:18432
	ds_read_b128 v[174:177], v205 offset:19456
	ds_read_b128 v[178:181], v205 offset:20480
	ds_read_b128 v[192:195], v205 offset:21504
	ds_read_b128 v[196:199], v205 offset:22528
	ds_read_b128 v[224:227], v205 offset:23552
	global_load_lds_dwordx4 v[200:201], off
	s_add_i32 m0, s26, 0x2000
	s_add_u32 s26, s28, 0x160000
	v_lshl_add_u64 v[206:207], s[28:29], 0, v[182:183]
	s_addc_u32 s27, s29, 0
	s_add_i32 s87, s88, s45
	global_load_lds_dwordx4 v[206:207], off
	v_lshl_add_u64 v[216:217], s[26:27], 0, v[16:17]
	s_mov_b32 m0, s87
	v_lshl_add_u64 v[228:229], s[40:41], 0, v[184:185]
	global_load_lds_dwordx4 v[216:217], off
	v_lshl_add_u64 v[216:217], s[26:27], 0, v[182:183]
	s_add_i32 m0, s87, 0x2000
	s_nop 0
	global_load_lds_dwordx4 v[216:217], off
	v_lshl_add_u64 v[216:217], s[40:41], 0, v[186:187]
	s_mov_b32 m0, s47
	s_nop 0
	global_load_lds_dwordx4 v[216:217], off
	s_mov_b32 m0, s48
	s_nop 0
	global_load_lds_dwordx4 v[228:229], off
	s_waitcnt vmcnt(8)
	s_waitcnt lgkmcnt(0)
	s_barrier
	s_nop 0
	s_waitcnt lgkmcnt(0)
	v_mfma_f32_16x16x32_bf16 v[62:65], v[130:133], v[162:165], v[62:65]
	v_mfma_f32_16x16x32_bf16 v[58:61], v[138:141], v[162:165], v[58:61]
	v_mfma_f32_16x16x32_bf16 v[50:53], v[130:133], v[170:173], v[50:53]
	v_mfma_f32_16x16x32_bf16 v[42:45], v[138:141], v[170:173], v[42:45]
	v_mfma_f32_16x16x32_bf16 v[34:37], v[130:133], v[178:181], v[34:37]
	v_mfma_f32_16x16x32_bf16 v[26:29], v[138:141], v[178:181], v[26:29]
	v_mfma_f32_16x16x32_bf16 v[18:21], v[130:133], v[196:199], v[18:21]
	v_mfma_f32_16x16x32_bf16 v[8:11], v[138:141], v[196:199], v[8:11]
	v_mfma_f32_16x16x32_bf16 v[62:65], v[134:137], v[166:169], v[62:65]
	v_mfma_f32_16x16x32_bf16 v[58:61], v[142:145], v[166:169], v[58:61]
	v_mfma_f32_16x16x32_bf16 v[50:53], v[134:137], v[174:177], v[50:53]
	v_mfma_f32_16x16x32_bf16 v[42:45], v[142:145], v[174:177], v[42:45]
	v_mfma_f32_16x16x32_bf16 v[34:37], v[134:137], v[192:195], v[34:37]
	v_mfma_f32_16x16x32_bf16 v[26:29], v[142:145], v[192:195], v[26:29]
	v_mfma_f32_16x16x32_bf16 v[18:21], v[134:137], v[224:227], v[18:21]
	v_mfma_f32_16x16x32_bf16 v[8:11], v[142:145], v[224:227], v[8:11]
	s_nop 0
	s_nop 0
	v_mfma_f32_16x16x32_bf16 v[54:57], v[146:149], v[162:165], v[54:57]
	v_mfma_f32_16x16x32_bf16 v[46:49], v[154:157], v[162:165], v[46:49]
	v_mfma_f32_16x16x32_bf16 v[38:41], v[146:149], v[170:173], v[38:41]
	v_mfma_f32_16x16x32_bf16 v[30:33], v[154:157], v[170:173], v[30:33]
	v_mfma_f32_16x16x32_bf16 v[22:25], v[146:149], v[178:181], v[22:25]
	v_mfma_f32_16x16x32_bf16 v[12:15], v[154:157], v[178:181], v[12:15]
	v_mfma_f32_16x16x32_bf16 v[4:7], v[146:149], v[196:199], v[4:7]
	v_mfma_f32_16x16x32_bf16 v[0:3], v[154:157], v[196:199], v[0:3]
	v_mfma_f32_16x16x32_bf16 v[54:57], v[150:153], v[166:169], v[54:57]
	v_mfma_f32_16x16x32_bf16 v[46:49], v[158:161], v[166:169], v[46:49]
	v_mfma_f32_16x16x32_bf16 v[38:41], v[150:153], v[174:177], v[38:41]
	v_mfma_f32_16x16x32_bf16 v[30:33], v[158:161], v[174:177], v[30:33]
	v_mfma_f32_16x16x32_bf16 v[22:25], v[150:153], v[192:195], v[22:25]
	v_mfma_f32_16x16x32_bf16 v[12:15], v[158:161], v[192:195], v[12:15]
	v_mfma_f32_16x16x32_bf16 v[4:7], v[150:153], v[224:227], v[4:7]
	v_mfma_f32_16x16x32_bf16 v[0:3], v[158:161], v[224:227], v[0:3]
	s_nop 0
	s_barrier
	s_add_i32 s87, 0, 0x18000
	s_add_i32 s88, 0, 0x1c000
	v_add_u32_e32 v142, s87, v203
	v_add_u32_e32 v158, s88, v203
	ds_read_b128 v[130:133], v142
	ds_read_b128 v[134:137], v142 offset:1024
	ds_read_b128 v[138:141], v142 offset:2048
	ds_read_b128 v[142:145], v142 offset:3072
	ds_read_b128 v[146:149], v158
	ds_read_b128 v[150:153], v158 offset:1024
	ds_read_b128 v[154:157], v158 offset:2048
	ds_read_b128 v[158:161], v158 offset:3072
	s_add_u32 s26, s40, 0x160000
	s_addc_u32 s27, s41, 0
	s_mov_b32 m0, s49
	v_lshl_add_u64 v[230:231], s[26:27], 0, v[186:187]
	ds_read_b128 v[162:165], v205 offset:32768
	ds_read_b128 v[166:169], v205 offset:33792
	ds_read_b128 v[170:173], v205 offset:34816
	ds_read_b128 v[174:177], v205 offset:35840
	ds_read_b128 v[178:181], v205 offset:36864
	ds_read_b128 v[192:195], v205 offset:37888
	ds_read_b128 v[196:199], v205 offset:38912
	ds_read_b128 v[224:227], v205 offset:39936
	global_load_lds_dwordx4 v[230:231], off
	v_lshl_add_u64 v[230:231], s[26:27], 0, v[184:185]
	s_mov_b32 m0, s50
	s_nop 0
	global_load_lds_dwordx4 v[230:231], off
	s_waitcnt vmcnt(8)
	s_waitcnt lgkmcnt(0)
	s_barrier
	s_nop 0
	s_waitcnt lgkmcnt(0)
	v_mfma_f32_16x16x32_bf16 v[126:129], v[130:133], v[162:165], v[126:129]
	v_mfma_f32_16x16x32_bf16 v[122:125], v[138:141], v[162:165], v[122:125]
	v_mfma_f32_16x16x32_bf16 v[114:117], v[130:133], v[170:173], v[114:117]
	v_mfma_f32_16x16x32_bf16 v[106:109], v[138:141], v[170:173], v[106:109]
	v_mfma_f32_16x16x32_bf16 v[98:101], v[130:133], v[178:181], v[98:101]
	v_mfma_f32_16x16x32_bf16 v[90:93], v[138:141], v[178:181], v[90:93]
	v_mfma_f32_16x16x32_bf16 v[82:85], v[130:133], v[196:199], v[82:85]
	v_mfma_f32_16x16x32_bf16 v[74:77], v[138:141], v[196:199], v[74:77]
	v_mfma_f32_16x16x32_bf16 v[126:129], v[134:137], v[166:169], v[126:129]
	v_mfma_f32_16x16x32_bf16 v[122:125], v[142:145], v[166:169], v[122:125]
	v_mfma_f32_16x16x32_bf16 v[114:117], v[134:137], v[174:177], v[114:117]
	v_mfma_f32_16x16x32_bf16 v[106:109], v[142:145], v[174:177], v[106:109]
	v_mfma_f32_16x16x32_bf16 v[98:101], v[134:137], v[192:195], v[98:101]
	v_mfma_f32_16x16x32_bf16 v[90:93], v[142:145], v[192:195], v[90:93]
	v_mfma_f32_16x16x32_bf16 v[82:85], v[134:137], v[224:227], v[82:85]
	v_mfma_f32_16x16x32_bf16 v[74:77], v[142:145], v[224:227], v[74:77]
	s_nop 0
	s_nop 0
	v_mfma_f32_16x16x32_bf16 v[118:121], v[146:149], v[162:165], v[118:121]
	v_mfma_f32_16x16x32_bf16 v[110:113], v[154:157], v[162:165], v[110:113]
	v_mfma_f32_16x16x32_bf16 v[102:105], v[146:149], v[170:173], v[102:105]
	v_mfma_f32_16x16x32_bf16 v[94:97], v[154:157], v[170:173], v[94:97]
	v_mfma_f32_16x16x32_bf16 v[86:89], v[146:149], v[178:181], v[86:89]
	v_mfma_f32_16x16x32_bf16 v[78:81], v[154:157], v[178:181], v[78:81]
	v_mfma_f32_16x16x32_bf16 v[70:73], v[146:149], v[196:199], v[70:73]
	v_mfma_f32_16x16x32_bf16 v[66:69], v[154:157], v[196:199], v[66:69]
	v_mfma_f32_16x16x32_bf16 v[118:121], v[150:153], v[166:169], v[118:121]
	v_mfma_f32_16x16x32_bf16 v[110:113], v[158:161], v[166:169], v[110:113]
	v_mfma_f32_16x16x32_bf16 v[102:105], v[150:153], v[174:177], v[102:105]
	v_mfma_f32_16x16x32_bf16 v[94:97], v[158:161], v[174:177], v[94:97]
	v_mfma_f32_16x16x32_bf16 v[86:89], v[150:153], v[192:195], v[86:89]
	v_mfma_f32_16x16x32_bf16 v[78:81], v[158:161], v[192:195], v[78:81]
	v_mfma_f32_16x16x32_bf16 v[70:73], v[150:153], v[224:227], v[70:73]
	v_mfma_f32_16x16x32_bf16 v[66:69], v[158:161], v[224:227], v[66:69]
	s_nop 0
	s_barrier
	s_add_i32 s26, s87, s45
	v_lshl_add_u64 v[200:201], v[200:201], 0, s[34:35]
	s_mov_b32 m0, s26
	ds_read_b128 v[162:165], v205 offset:49152
	ds_read_b128 v[166:169], v205 offset:50176
	ds_read_b128 v[170:173], v205 offset:51200
	ds_read_b128 v[174:177], v205 offset:52224
	ds_read_b128 v[178:181], v205 offset:53248
	ds_read_b128 v[192:195], v205 offset:54272
	ds_read_b128 v[196:199], v205 offset:55296
	ds_read_b128 v[224:227], v205 offset:56320
	global_load_lds_dwordx4 v[200:201], off
	s_add_i32 m0, s26, 0x2000
	s_add_u32 s26, s28, 0x160080
	v_lshl_add_u64 v[200:201], v[206:207], 0, s[34:35]
	s_addc_u32 s27, s29, 0
	s_add_i32 s28, s88, s45
	global_load_lds_dwordx4 v[200:201], off
	v_lshl_add_u64 v[200:201], s[26:27], 0, v[16:17]
	s_mov_b32 m0, s28
	s_nop 0
	global_load_lds_dwordx4 v[200:201], off
	v_lshl_add_u64 v[200:201], s[26:27], 0, v[182:183]
	s_add_i32 m0, s28, 0x2000
	s_nop 0
	global_load_lds_dwordx4 v[200:201], off
	v_lshl_add_u64 v[200:201], v[216:217], 0, s[34:35]
	s_mov_b32 m0, s53
	s_nop 0
	global_load_lds_dwordx4 v[200:201], off
	v_lshl_add_u64 v[200:201], v[228:229], 0, s[34:35]
	s_mov_b32 m0, s57
	s_nop 0
	global_load_lds_dwordx4 v[200:201], off
	s_waitcnt vmcnt(8)
	s_waitcnt lgkmcnt(0)
	s_barrier
	s_nop 0
	s_waitcnt lgkmcnt(0)
	v_mfma_f32_16x16x32_bf16 v[62:65], v[130:133], v[162:165], v[62:65]
	v_mfma_f32_16x16x32_bf16 v[58:61], v[138:141], v[162:165], v[58:61]
	v_mfma_f32_16x16x32_bf16 v[50:53], v[130:133], v[170:173], v[50:53]
	v_mfma_f32_16x16x32_bf16 v[42:45], v[138:141], v[170:173], v[42:45]
	v_mfma_f32_16x16x32_bf16 v[34:37], v[130:133], v[178:181], v[34:37]
	v_mfma_f32_16x16x32_bf16 v[26:29], v[138:141], v[178:181], v[26:29]
	v_mfma_f32_16x16x32_bf16 v[18:21], v[130:133], v[196:199], v[18:21]
	v_mfma_f32_16x16x32_bf16 v[8:11], v[138:141], v[196:199], v[8:11]
	v_mfma_f32_16x16x32_bf16 v[62:65], v[134:137], v[166:169], v[62:65]
	v_mfma_f32_16x16x32_bf16 v[58:61], v[142:145], v[166:169], v[58:61]
	v_mfma_f32_16x16x32_bf16 v[50:53], v[134:137], v[174:177], v[50:53]
	v_mfma_f32_16x16x32_bf16 v[42:45], v[142:145], v[174:177], v[42:45]
	v_mfma_f32_16x16x32_bf16 v[34:37], v[134:137], v[192:195], v[34:37]
	v_mfma_f32_16x16x32_bf16 v[26:29], v[142:145], v[192:195], v[26:29]
	v_mfma_f32_16x16x32_bf16 v[18:21], v[134:137], v[224:227], v[18:21]
	v_mfma_f32_16x16x32_bf16 v[8:11], v[142:145], v[224:227], v[8:11]
	s_nop 0
	s_nop 0
	v_mfma_f32_16x16x32_bf16 v[54:57], v[146:149], v[162:165], v[54:57]
	v_mfma_f32_16x16x32_bf16 v[46:49], v[154:157], v[162:165], v[46:49]
	v_mfma_f32_16x16x32_bf16 v[38:41], v[146:149], v[170:173], v[38:41]
	v_mfma_f32_16x16x32_bf16 v[30:33], v[154:157], v[170:173], v[30:33]
	v_mfma_f32_16x16x32_bf16 v[22:25], v[146:149], v[178:181], v[22:25]
	v_mfma_f32_16x16x32_bf16 v[12:15], v[154:157], v[178:181], v[12:15]
	v_mfma_f32_16x16x32_bf16 v[4:7], v[146:149], v[196:199], v[4:7]
	v_mfma_f32_16x16x32_bf16 v[0:3], v[154:157], v[196:199], v[0:3]
	v_mfma_f32_16x16x32_bf16 v[54:57], v[150:153], v[166:169], v[54:57]
	v_mfma_f32_16x16x32_bf16 v[46:49], v[158:161], v[166:169], v[46:49]
	v_mfma_f32_16x16x32_bf16 v[38:41], v[150:153], v[174:177], v[38:41]
	v_mfma_f32_16x16x32_bf16 v[30:33], v[158:161], v[174:177], v[30:33]
	v_mfma_f32_16x16x32_bf16 v[22:25], v[150:153], v[192:195], v[22:25]
	v_mfma_f32_16x16x32_bf16 v[12:15], v[158:161], v[192:195], v[12:15]
	v_mfma_f32_16x16x32_bf16 v[4:7], v[150:153], v[224:227], v[4:7]
	v_mfma_f32_16x16x32_bf16 v[0:3], v[158:161], v[224:227], v[0:3]
	s_nop 0
	s_barrier
	s_add_i32 s86, s86, 2
	s_add_u32 s42, s42, 0x100
	s_addc_u32 s43, s43, 0
	s_cmpk_gt_u32 s86, 0x55
	s_mov_b64 s[26:27], s[36:37]
	s_cbranch_scc0 .LBB0_992
	s_and_b64 vcc, exec, s[14:15]
	s_cbranch_vccz .LBB0_995
	s_barrier

.LBB0_1000:
	s_setprio 0
	s_waitcnt vmcnt(0)
	s_barrier
	v_readlane_b32 s83, v255, 41
	s_cmp_lg_u32 s83, 0
	s_cbranch_scc1 .LBB0_1001
	s_cmp_gt_u32 s60, 64
	s_cselect_b32 s84, 64, 0
	s_cmp_lt_u32 s2, s84
	s_cbranch_scc1 .LBB0_1001
	s_sub_u32 s2, s2, s84
	s_sub_u32 s60, s60, s84
	v_writelane_b32 v255, s84, 47
	v_readlane_b32 s62, v255, 37
	v_readlane_b32 s63, v255, 38
	v_readlane_b32 s18, v255, 8
	v_readlane_b32 s19, v255, 9
	s_load_dwordx4 s[48:51], s[18:19], 0x48
	s_load_dwordx2 s[0:1], s[18:19], 0x68
	s_load_dwordx2 s[38:39], s[18:19], 0x88
	s_load_dwordx2 s[22:23], s[18:19], 0x98
	s_load_dwordx8 s[40:47], s[18:19], 0xb8
	s_load_dwordx4 s[56:59], s[18:19], 0xd8
	s_nop 0
	s_load_dwordx2 s[18:19], s[18:19], 0xf0
	v_mov_b32_e32 v0, v208
	s_mov_b32 s24, s2
	s_cmpk_gt_i32 s24, 0x3ff
	s_cbranch_scc1 .LBB0_96
	s_waitcnt lgkmcnt(0)
	s_add_u32 s48, s48, 0x2000000
	s_addc_u32 s49, s49, 0
	s_ashr_i32 s26, s24, 31
	s_lshr_b32 s26, s26, 28
	s_add_i32 s26, s24, s26
	s_lshl_b32 s27, s26, 2
	s_and_b32 s26, s26, 0x1fffff0
	v_ashrrev_i32_e32 v23, 6, v0
	s_sub_i32 s26, s24, s26
	v_mov_b32_e32 v1, s27
	s_movk_i32 s27, 0xffc0
	v_bfi_b32 v2, s27, v1, v0
	v_lshl_add_u32 v4, s26, 7, v23
	v_ashrrev_i32_e32 v3, 31, v2
	v_ashrrev_i32_e32 v5, 31, v4
	v_lshl_add_u64 v[2:3], v[2:3], 2, s[48:49]
	v_lshlrev_b64 v[4:5], 14, v[4:5]
	v_lshl_add_u64 v[2:3], v[2:3], 0, v[4:5]
	v_add_co_u32_e32 v4, vcc, s17, v2
	s_mov_b32 s26, 0xe0000
	s_nop 0
	v_addc_co_u32_e32 v5, vcc, 0, v3, vcc
	v_add_co_u32_e32 v6, vcc, s20, v2
	v_and_b32_e32 v20, 63, v0
	s_nop 0
	v_addc_co_u32_e32 v7, vcc, 0, v3, vcc
	v_add_co_u32_e32 v8, vcc, s21, v2
	v_ashrrev_i32_e32 v21, 4, v0
	s_nop 0
	v_addc_co_u32_e32 v9, vcc, 0, v3, vcc
	v_add_co_u32_e32 v10, vcc, s64, v2
	v_lshlrev_b32_e32 v0, 3, v0
	s_waitcnt vmcnt(6)
	v_addc_co_u32_e32 v11, vcc, 0, v3, vcc
	s_waitcnt vmcnt(5)
	v_add_co_u32_e32 v12, vcc, s65, v2
	v_and_b32_e32 v22, 0x78, v0
	s_waitcnt vmcnt(4)
	v_addc_co_u32_e32 v13, vcc, 0, v3, vcc
	v_add_co_u32_e32 v14, vcc, s66, v2
	s_waitcnt vmcnt(3)
	v_lshlrev_b32_e32 v16, 1, v22
	s_waitcnt vmcnt(2)
	v_addc_co_u32_e32 v15, vcc, 0, v3, vcc
	v_add_co_u32_e32 v24, vcc, s26, v2
	s_mov_b32 s26, 0x100000
	s_nop 0
	v_addc_co_u32_e32 v25, vcc, 0, v3, vcc
	v_add_co_u32_e32 v26, vcc, s26, v2
	s_mov_b32 s26, 0x120000
	s_nop 0
	v_addc_co_u32_e32 v27, vcc, 0, v3, vcc
	v_add_co_u32_e32 v28, vcc, s26, v2
	s_mov_b32 s26, 0x140000
	s_nop 0
	v_addc_co_u32_e32 v29, vcc, 0, v3, vcc
	v_add_co_u32_e32 v30, vcc, s26, v2
	s_mov_b32 s26, 0x160000
	s_nop 0
	v_addc_co_u32_e32 v31, vcc, 0, v3, vcc
	v_add_co_u32_e32 v32, vcc, s26, v2
	s_mov_b32 s26, 0x180000
	s_nop 0
	v_addc_co_u32_e32 v33, vcc, 0, v3, vcc
	v_add_co_u32_e32 v34, vcc, s26, v2
	s_mov_b32 s26, 0x1a0000
	s_nop 0
	v_addc_co_u32_e32 v35, vcc, 0, v3, vcc
	v_add_co_u32_e32 v36, vcc, s26, v2
	s_mov_b32 s26, 0x1c0000
	s_nop 0
	v_addc_co_u32_e32 v37, vcc, 0, v3, vcc
	v_add_co_u32_e32 v38, vcc, s26, v2
	s_mov_b32 s26, 0x1e0000
	s_nop 0
	v_addc_co_u32_e32 v39, vcc, 0, v3, vcc
	v_add_co_u32_e32 v40, vcc, s26, v2
	v_lshl_add_u64 v[0:1], s[18:19], 0, v[16:17]
	s_mov_b64 s[26:27], 0x378000
	v_addc_co_u32_e32 v41, vcc, 0, v3, vcc
	v_lshl_add_u64 v[18:19], v[0:1], 0, s[26:27]
	global_load_dword v0, v[2:3], off nt
	global_load_dword v1, v[4:5], off nt
	s_nop 0
	global_load_dword v2, v[6:7], off nt
	global_load_dword v3, v[8:9], off nt
	global_load_dword v4, v[10:11], off nt
	global_load_dword v5, v[12:13], off nt
	s_nop 0
	global_load_dword v6, v[14:15], off nt
	global_load_dword v7, v[24:25], off nt
	global_load_dword v8, v[26:27], off nt
	global_load_dword v9, v[28:29], off nt
	global_load_dword v10, v[30:31], off nt
	global_load_dword v11, v[32:33], off nt
	global_load_dword v12, v[34:35], off nt
	global_load_dword v13, v[36:37], off nt
	global_load_dword v14, v[38:39], off nt
	global_load_dword v15, v[40:41], off nt
	s_movk_i32 s26, 0x104
	s_lshl_b32 s27, s60, 7
	v_mul_lo_u32 v16, v23, s26
	v_mul_u32_u24_e32 v22, 0x104, v22
	s_lshl_b32 s26, s24, 7
	v_add_u32_e32 v23, s27, v23
	s_mov_b64 s[52:53], 0
	s_branch .LBB0_94
